# indexer: next-tile key fragment prefetch no longer waited for right after issue (older loads drained before the prefetch, wait moved to first use) in three tile blocks; relu as a single v_max in the h
# speedup vs baseline: 1.0259x; 1.0040x over previous
; DI void a1_task(unsigned char* shm, const bf16_t* prm, const bf16_t* prt, unsigned* mask, int b, int qt, const int tid) {
;     ...
;     for (int jt = 0; jt < 8; ++jt) {
;         const int kt = wid + 8 * jt;
;         if (kt <= qt) {
;             const int s0 = kt * 32;
;             bf16x8 kn[4];
;             const bool hn = (jt < 7) && (kt + 8 <= qt);
;             if (hn) {
; #pragma unroll
;                 for (int ks = 0; ks < 4; ++ks) kn[ks] = *(const bf16x8*)(kp + (size_t)(s0 + 256) * RM_LD + 16 * ks);
;             }
.LBB0_385:
	s_cmp_ge_i32 s2, s6
	s_cselect_b64 s[4:5], -1, 0
	v_writelane_b32 v255, s4, 38
	s_and_b64 vcc, exec, s[4:5]
	v_or_b32_e32 v0, s0, v100
	v_writelane_b32 v255, s5, 39
	s_mov_b32 s4, s6
	v_writelane_b32 v255, s4, 40
	s_mov_b64 s[0:1], -1
	v_readfirstlane_b32 s40, v0
	v_writelane_b32 v255, s5, 41
	s_cbranch_vccz .LBB0_393
	s_lshl_b32 s0, s6, 5
	s_add_i32 s4, s6, 8
	s_cmp_le_i32 s4, s2
	s_cselect_b64 vcc, -1, 0
	s_mov_b32 s40, s4
	s_waitcnt vmcnt(0)
	s_cmp_gt_i32 s4, s2
	s_cbranch_scc1 .LBB0_388
	s_add_i32 s1, s0, 0x100
	v_mad_i64_i32 v[2:3], s[4:5], s1, v241, v[108:109]
	global_load_dwordx4 v[18:21], v[2:3], off offset:1920
	global_load_dwordx4 v[22:25], v[2:3], off offset:1952
	global_load_dwordx4 v[26:29], v[2:3], off offset:1984
	global_load_dwordx4 v[30:33], v[2:3], off offset:2016

; #define MFMA32(a, b, c) __builtin_amdgcn_mfma_f32_32x32x16_bf16((a), (b), (c), 0, 0, 0)
; DI void a1_task(unsigned char* shm, const bf16_t* prm, const bf16_t* prt, unsigned* mask, int b, int qt, const int tid) {
;     ...
;             for (int hh = 0; hh < 8; ++hh) {
;                 bf16x8 qa[4];
; #pragma unroll
;                 for (int ks = 0; ks < 4; ++ks) qa[ks] = *(const bf16x8*)(qb0 + hh * 128 + 32 * ks);
;                 const float wv = wqs[hh * 32 + r];
;                 asm volatile("s_waitcnt lgkmcnt(0)" ::: "memory");
;                 f32x16 acc;
; #pragma unroll
;                 for (int i = 0; i < 16; ++i) acc[i] = 0.f;
; #pragma unroll
;                 for (int ks = 0; ks < 4; ++ks) acc = MFMA32(kf[ks], qa[ks], acc);
; #pragma unroll
;                 for (int i = 0; i < 16; ++i) idx[i] = fmaf(wv, fmaxf(acc[i], 0.f), idx[i]);
;             }
;     ...
;             if (hn) {
; #pragma unroll
;                 for (int ks = 0; ks < 4; ++ks) kf[ks] = kn[ks];
;             }
.LBB0_389:
	v_add_u32_e32 v79, s1, v118
	ds_read_b128 v[2:5], v79
	ds_read_b128 v[66:69], v79 offset:32
	ds_read_b128 v[70:73], v79 offset:64
	ds_read_b128 v[74:77], v79 offset:96
	v_add_u32_e32 v80, s1, v135
	s_waitcnt lgkmcnt(3)
	v_mfma_f32_32x32x16_bf16 v[2:17], v[50:53], v[2:5], 0
	ds_read_b32 v78, v80
	s_waitcnt lgkmcnt(0)
	s_addk_i32 s1, 0x100
	s_cmpk_eq_i32 s1, 0x400
	s_waitcnt lgkmcnt(3)
	v_mfma_f32_32x32x16_bf16 v[2:17], v[54:57], v[66:69], v[2:17]
	s_waitcnt lgkmcnt(2)
	v_mfma_f32_32x32x16_bf16 v[2:17], v[58:61], v[70:73], v[2:17]
	s_waitcnt lgkmcnt(1)
	v_mfma_f32_32x32x16_bf16 v[2:17], v[62:65], v[74:77], v[2:17]
	s_nop 11
	v_max_f32_e32 v2, 0, v2
	v_max_f32_e32 v3, 0, v3
	s_waitcnt lgkmcnt(0)
	v_pk_fma_f32 v[48:49], v[78:79], v[2:3], v[48:49] op_sel_hi:[0,1,1]
	v_max_f32_e32 v2, 0, v4
	v_max_f32_e32 v3, 0, v5
	v_pk_fma_f32 v[46:47], v[78:79], v[2:3], v[46:47] op_sel_hi:[0,1,1]
	v_max_f32_e32 v2, 0, v6
	v_max_f32_e32 v3, 0, v7
	v_pk_fma_f32 v[44:45], v[78:79], v[2:3], v[44:45] op_sel_hi:[0,1,1]
	v_max_f32_e32 v2, 0, v8
	v_max_f32_e32 v3, 0, v9
	v_pk_fma_f32 v[42:43], v[78:79], v[2:3], v[42:43] op_sel_hi:[0,1,1]
	v_max_f32_e32 v2, 0, v10
	v_max_f32_e32 v3, 0, v11
	v_pk_fma_f32 v[40:41], v[78:79], v[2:3], v[40:41] op_sel_hi:[0,1,1]
	v_max_f32_e32 v2, 0, v12
	v_max_f32_e32 v3, 0, v13
	v_pk_fma_f32 v[38:39], v[78:79], v[2:3], v[38:39] op_sel_hi:[0,1,1]
	v_max_f32_e32 v2, 0, v14
	v_max_f32_e32 v3, 0, v15
	v_pk_fma_f32 v[36:37], v[78:79], v[2:3], v[36:37] op_sel_hi:[0,1,1]
	v_max_f32_e32 v2, 0, v16
	v_max_f32_e32 v3, 0, v17
	v_pk_fma_f32 v[34:35], v[78:79], v[2:3], v[34:35] op_sel_hi:[0,1,1]
	ds_read_b128 v[2:5], v79 offset:128
	ds_read_b128 v[66:69], v79 offset:160
	ds_read_b128 v[70:73], v79 offset:192
	ds_read_b128 v[74:77], v79 offset:224
	ds_read_b32 v78, v80 offset:128
	s_waitcnt lgkmcnt(4)
	v_mfma_f32_32x32x16_bf16 v[2:17], v[50:53], v[2:5], 0
	s_waitcnt lgkmcnt(0)
	s_waitcnt lgkmcnt(3)
	v_mfma_f32_32x32x16_bf16 v[2:17], v[54:57], v[66:69], v[2:17]
	s_waitcnt lgkmcnt(2)
	v_mfma_f32_32x32x16_bf16 v[2:17], v[58:61], v[70:73], v[2:17]
	s_waitcnt lgkmcnt(1)
	v_mfma_f32_32x32x16_bf16 v[2:17], v[62:65], v[74:77], v[2:17]
	s_nop 11
	v_max_f32_e32 v2, 0, v2
	v_max_f32_e32 v3, 0, v3
	s_waitcnt lgkmcnt(0)
	v_pk_fma_f32 v[48:49], v[78:79], v[2:3], v[48:49] op_sel_hi:[0,1,1]
	v_max_f32_e32 v2, 0, v4
	v_max_f32_e32 v3, 0, v5
	v_pk_fma_f32 v[46:47], v[78:79], v[2:3], v[46:47] op_sel_hi:[0,1,1]
	v_max_f32_e32 v2, 0, v6
	v_max_f32_e32 v3, 0, v7
	v_pk_fma_f32 v[44:45], v[78:79], v[2:3], v[44:45] op_sel_hi:[0,1,1]
	v_max_f32_e32 v2, 0, v8
	v_max_f32_e32 v3, 0, v9
	v_pk_fma_f32 v[42:43], v[78:79], v[2:3], v[42:43] op_sel_hi:[0,1,1]
	v_max_f32_e32 v2, 0, v10
	v_max_f32_e32 v3, 0, v11
	v_pk_fma_f32 v[40:41], v[78:79], v[2:3], v[40:41] op_sel_hi:[0,1,1]
	v_max_f32_e32 v2, 0, v12
	v_max_f32_e32 v3, 0, v13
	v_pk_fma_f32 v[38:39], v[78:79], v[2:3], v[38:39] op_sel_hi:[0,1,1]
	v_max_f32_e32 v2, 0, v14
	v_max_f32_e32 v3, 0, v15
	v_pk_fma_f32 v[36:37], v[78:79], v[2:3], v[36:37] op_sel_hi:[0,1,1]
	v_max_f32_e32 v2, 0, v16
	v_max_f32_e32 v3, 0, v17
	v_pk_fma_f32 v[34:35], v[78:79], v[2:3], v[34:35] op_sel_hi:[0,1,1]
	s_cbranch_scc0 .LBB0_389
	v_or_b32_e32 v66, s0, v98
	v_or_b32_e32 v2, 3, v66
	v_or_b32_e32 v3, 2, v66
	v_cmp_le_i32_e64 s[92:93], v3, v0
	v_cmp_le_i32_e64 s[94:95], v2, v0
	v_or_b32_e32 v2, 5, v66
	v_or_b32_e32 v3, 4, v66
	v_cmp_le_i32_e64 s[84:85], v3, v0
	v_cmp_le_i32_e64 s[86:87], v2, v0
	v_or_b32_e32 v2, 7, v66
	v_or_b32_e32 v3, 6, v66
	v_cmp_le_i32_e64 s[76:77], v3, v0
	v_cmp_le_i32_e64 s[78:79], v2, v0
	v_or_b32_e32 v2, 17, v66
	v_or_b32_e32 v3, 16, v66
	v_cmp_le_i32_e64 s[68:69], v3, v0
	v_cmp_le_i32_e64 s[70:71], v2, v0
	v_or_b32_e32 v2, 19, v66
	v_or_b32_e32 v3, 18, v66
	v_cmp_le_i32_e64 s[60:61], v3, v0
	v_cmp_le_i32_e64 s[62:63], v2, v0
	v_or_b32_e32 v2, 21, v66
	v_or_b32_e32 v3, 20, v66
	v_cmp_le_i32_e64 s[52:53], v3, v0
	v_cmp_le_i32_e64 s[54:55], v2, v0
	v_pk_add_f32 v[2:3], v[34:35], 0 op_sel_hi:[1,0]
	v_or_b32_e32 v34, 23, v66
	v_or_b32_e32 v35, 22, v66
	v_pk_add_f32 v[16:17], v[48:49], 0 op_sel_hi:[1,0]
	v_pk_add_f32 v[14:15], v[46:47], 0 op_sel_hi:[1,0]
	v_pk_add_f32 v[12:13], v[44:45], 0 op_sel_hi:[1,0]
	v_pk_add_f32 v[10:11], v[42:43], 0 op_sel_hi:[1,0]
	v_pk_add_f32 v[8:9], v[40:41], 0 op_sel_hi:[1,0]
	v_pk_add_f32 v[6:7], v[38:39], 0 op_sel_hi:[1,0]
	v_pk_add_f32 v[4:5], v[36:37], 0 op_sel_hi:[1,0]
	v_cmp_le_i32_e64 s[42:43], v35, v0
	v_cmp_le_i32_e64 s[44:45], v34, v0
	v_mov_b64_e32 v[34:35], v[50:51]
	v_mov_b64_e32 v[38:39], v[54:55]
	v_mov_b64_e32 v[42:43], v[58:59]
	v_mov_b64_e32 v[46:47], v[62:63]
	v_cmp_gt_i32_e64 s[46:47], 0, v17
	v_cmp_gt_i32_e64 s[6:7], 0, v16
	v_cmp_le_i32_e64 s[8:9], v66, v0
	v_cmp_lt_i32_e64 s[4:5], v66, v0
	v_cmp_gt_i32_e64 s[90:91], 0, v14
	v_cmp_gt_i32_e64 s[96:97], 0, v15
	v_cmp_gt_i32_e64 s[82:83], 0, v12
	v_cmp_gt_i32_e64 s[88:89], 0, v13
	v_cmp_gt_i32_e64 s[74:75], 0, v10
	v_cmp_gt_i32_e64 s[80:81], 0, v11
	v_cmp_gt_i32_e64 s[66:67], 0, v8
	v_cmp_gt_i32_e64 s[72:73], 0, v9
	v_cmp_gt_i32_e64 s[58:59], 0, v6
	v_cmp_gt_i32_e64 s[64:65], 0, v7
	v_cmp_gt_i32_e64 s[50:51], 0, v4
	v_cmp_gt_i32_e64 s[56:57], 0, v5
	v_cmp_gt_i32_e64 s[0:1], 0, v2
	v_cmp_gt_i32_e64 s[48:49], 0, v3
	s_and_b64 vcc, exec, vcc
	v_mov_b64_e32 v[36:37], v[52:53]
	v_mov_b64_e32 v[40:41], v[56:57]
	v_mov_b64_e32 v[44:45], v[60:61]
	v_mov_b64_e32 v[48:49], v[64:65]
	s_cbranch_vccz .LBB0_392
	s_waitcnt vmcnt(0)
	v_mov_b64_e32 v[36:37], v[20:21]
	v_mov_b64_e32 v[40:41], v[24:25]
	v_mov_b64_e32 v[44:45], v[28:29]
	v_mov_b64_e32 v[48:49], v[32:33]
	v_mov_b64_e32 v[34:35], v[18:19]
	v_mov_b64_e32 v[38:39], v[22:23]
	v_mov_b64_e32 v[42:43], v[26:27]
	v_mov_b64_e32 v[46:47], v[30:31]

; #define MFMA32(a, b, c) __builtin_amdgcn_mfma_f32_32x32x16_bf16((a), (b), (c), 0, 0, 0)
; DI void a1_task(unsigned char* shm, const bf16_t* prm, const bf16_t* prt, unsigned* mask, int b, int qt, const int tid) {
;     ...
;     for (int jt = 0; jt < 8; ++jt) {
;         const int kt = wid + 8 * jt;
;         if (kt <= qt) {
;             const int s0 = kt * 32;
;             bf16x8 kn[4];
;             const bool hn = (jt < 7) && (kt + 8 <= qt);
;             if (hn) {
; #pragma unroll
;                 for (int ks = 0; ks < 4; ++ks) kn[ks] = *(const bf16x8*)(kp + (size_t)(s0 + 256) * RM_LD + 16 * ks);
;             }
;             float idx[16];
; #pragma unroll
;             for (int i = 0; i < 16; ++i) idx[i] = 0.f;
;             const unsigned char* qb0 = shm + r * 1040 + 16 * h;
; #pragma unroll 2
;             for (int hh = 0; hh < 8; ++hh) {
;                 bf16x8 qa[4];
; #pragma unroll
;                 for (int ks = 0; ks < 4; ++ks) qa[ks] = *(const bf16x8*)(qb0 + hh * 128 + 32 * ks);
;                 const float wv = wqs[hh * 32 + r];
;                 asm volatile("s_waitcnt lgkmcnt(0)" ::: "memory");
;                 f32x16 acc;
; #pragma unroll
;                 for (int i = 0; i < 16; ++i) acc[i] = 0.f;
; #pragma unroll
;                 for (int ks = 0; ks < 4; ++ks) acc = MFMA32(kf[ks], qa[ks], acc);
; #pragma unroll
;                 for (int i = 0; i < 16; ++i) idx[i] = fmaf(wv, fmaxf(acc[i], 0.f), idx[i]);
;             }
;     ...
;             if (hn) {
; #pragma unroll
;                 for (int ks = 0; ks < 4; ++ks) kf[ks] = kn[ks];
;             }
.LBB0_395:
	s_cmp_le_i32 s40, s2
	s_cselect_b64 s[0:1], -1, 0
	v_writelane_b32 v255, s0, 42
	s_cmp_gt_i32 s40, s2
	v_mov_b32_e32 v158, 0
	v_writelane_b32 v255, s1, 43
	v_writelane_b32 v255, s40, 44
	s_nop 1
	v_writelane_b32 v255, s41, 45
	s_cbranch_scc1 .LBB0_403
	s_lshl_b32 s0, s40, 5
	s_add_i32 s1, s40, 8
	s_cmp_le_i32 s1, s2
	s_cselect_b64 s[40:41], -1, 0
	s_cmp_gt_i32 s1, s2
	s_cbranch_scc1 .LBB0_398
	s_add_i32 s1, s0, 0x100
	v_mad_i64_i32 v[2:3], s[4:5], s1, v241, v[108:109]
	global_load_dwordx4 v[18:21], v[2:3], off offset:1920
	global_load_dwordx4 v[22:25], v[2:3], off offset:1952
	global_load_dwordx4 v[26:29], v[2:3], off offset:1984
	global_load_dwordx4 v[30:33], v[2:3], off offset:2016
.LBB0_398:
	v_mov_b32_e32 v50, 0
	s_mov_b32 s1, 0
	v_mov_b32_e32 v51, v50
	v_mov_b32_e32 v64, v50
	v_mov_b32_e32 v65, v50
	v_mov_b32_e32 v62, v50
	v_mov_b32_e32 v63, v50
	v_mov_b32_e32 v60, v50
	v_mov_b32_e32 v61, v50
	v_mov_b32_e32 v58, v50
	v_mov_b32_e32 v59, v50
	v_mov_b32_e32 v56, v50
	v_mov_b32_e32 v57, v50
	v_mov_b32_e32 v54, v50
	v_mov_b32_e32 v55, v50
	v_mov_b32_e32 v52, v50
	v_mov_b32_e32 v53, v50
.LBB0_399:
	v_add_u32_e32 v79, s1, v118
	ds_read_b128 v[2:5], v79
	ds_read_b128 v[66:69], v79 offset:32
	ds_read_b128 v[70:73], v79 offset:64
	ds_read_b128 v[74:77], v79 offset:96
	v_add_u32_e32 v80, s1, v135
	s_waitcnt lgkmcnt(3)
	v_mfma_f32_32x32x16_bf16 v[2:17], v[34:37], v[2:5], 0
	ds_read_b32 v78, v80
	s_waitcnt lgkmcnt(0)
	s_addk_i32 s1, 0x100
	s_cmpk_lg_i32 s1, 0x400
	s_waitcnt lgkmcnt(3)
	v_mfma_f32_32x32x16_bf16 v[2:17], v[38:41], v[66:69], v[2:17]
	s_waitcnt lgkmcnt(2)
	v_mfma_f32_32x32x16_bf16 v[2:17], v[42:45], v[70:73], v[2:17]
	s_waitcnt lgkmcnt(1)
	v_mfma_f32_32x32x16_bf16 v[2:17], v[46:49], v[74:77], v[2:17]
	s_nop 11
	v_max_f32_e32 v2, 0, v2
	v_max_f32_e32 v3, 0, v3
	s_waitcnt lgkmcnt(0)
	v_pk_fma_f32 v[64:65], v[78:79], v[2:3], v[64:65] op_sel_hi:[0,1,1]
	v_max_f32_e32 v2, 0, v4
	v_max_f32_e32 v3, 0, v5
	v_pk_fma_f32 v[62:63], v[78:79], v[2:3], v[62:63] op_sel_hi:[0,1,1]
	v_max_f32_e32 v2, 0, v6
	v_max_f32_e32 v3, 0, v7
	v_pk_fma_f32 v[60:61], v[78:79], v[2:3], v[60:61] op_sel_hi:[0,1,1]
	v_max_f32_e32 v2, 0, v8
	v_max_f32_e32 v3, 0, v9
	v_pk_fma_f32 v[58:59], v[78:79], v[2:3], v[58:59] op_sel_hi:[0,1,1]
	v_max_f32_e32 v2, 0, v10
	v_max_f32_e32 v3, 0, v11
	v_pk_fma_f32 v[56:57], v[78:79], v[2:3], v[56:57] op_sel_hi:[0,1,1]
	v_max_f32_e32 v2, 0, v12
	v_max_f32_e32 v3, 0, v13
	v_pk_fma_f32 v[54:55], v[78:79], v[2:3], v[54:55] op_sel_hi:[0,1,1]
	v_max_f32_e32 v2, 0, v14
	v_max_f32_e32 v3, 0, v15
	v_pk_fma_f32 v[52:53], v[78:79], v[2:3], v[52:53] op_sel_hi:[0,1,1]
	v_max_f32_e32 v2, 0, v16
	v_max_f32_e32 v3, 0, v17
	v_pk_fma_f32 v[50:51], v[78:79], v[2:3], v[50:51] op_sel_hi:[0,1,1]
	ds_read_b128 v[2:5], v79 offset:128
	ds_read_b128 v[66:69], v79 offset:160
	ds_read_b128 v[70:73], v79 offset:192
	ds_read_b128 v[74:77], v79 offset:224
	ds_read_b32 v78, v80 offset:128
	s_waitcnt lgkmcnt(4)
	v_mfma_f32_32x32x16_bf16 v[2:17], v[34:37], v[2:5], 0
	s_waitcnt lgkmcnt(0)
	s_waitcnt lgkmcnt(3)
	v_mfma_f32_32x32x16_bf16 v[2:17], v[38:41], v[66:69], v[2:17]
	s_waitcnt lgkmcnt(2)
	v_mfma_f32_32x32x16_bf16 v[2:17], v[42:45], v[70:73], v[2:17]
	s_waitcnt lgkmcnt(1)
	v_mfma_f32_32x32x16_bf16 v[2:17], v[46:49], v[74:77], v[2:17]
	s_nop 11
	v_max_f32_e32 v2, 0, v2
	v_max_f32_e32 v3, 0, v3
	s_waitcnt lgkmcnt(0)
	v_pk_fma_f32 v[64:65], v[78:79], v[2:3], v[64:65] op_sel_hi:[0,1,1]
	v_max_f32_e32 v2, 0, v4
	v_max_f32_e32 v3, 0, v5
	v_pk_fma_f32 v[62:63], v[78:79], v[2:3], v[62:63] op_sel_hi:[0,1,1]
	v_max_f32_e32 v2, 0, v6
	v_max_f32_e32 v3, 0, v7
	v_pk_fma_f32 v[60:61], v[78:79], v[2:3], v[60:61] op_sel_hi:[0,1,1]
	v_max_f32_e32 v2, 0, v8
	v_max_f32_e32 v3, 0, v9
	v_pk_fma_f32 v[58:59], v[78:79], v[2:3], v[58:59] op_sel_hi:[0,1,1]
	v_max_f32_e32 v2, 0, v10
	v_max_f32_e32 v3, 0, v11
	v_pk_fma_f32 v[56:57], v[78:79], v[2:3], v[56:57] op_sel_hi:[0,1,1]
	v_max_f32_e32 v2, 0, v12
	v_max_f32_e32 v3, 0, v13
	v_pk_fma_f32 v[54:55], v[78:79], v[2:3], v[54:55] op_sel_hi:[0,1,1]
	v_max_f32_e32 v2, 0, v14
	v_max_f32_e32 v3, 0, v15
	v_pk_fma_f32 v[52:53], v[78:79], v[2:3], v[52:53] op_sel_hi:[0,1,1]
	v_max_f32_e32 v2, 0, v16
	v_max_f32_e32 v3, 0, v17
	v_pk_fma_f32 v[50:51], v[78:79], v[2:3], v[50:51] op_sel_hi:[0,1,1]
	s_cbranch_scc1 .LBB0_399
	v_or_b32_e32 v66, s0, v98
	v_or_b32_e32 v2, 3, v66
	v_or_b32_e32 v3, 2, v66
	v_cmp_le_i32_e64 s[92:93], v3, v0
	v_cmp_le_i32_e64 s[94:95], v2, v0
	v_or_b32_e32 v2, 5, v66
	v_or_b32_e32 v3, 4, v66
	v_cmp_le_i32_e64 s[84:85], v3, v0
	v_cmp_le_i32_e64 s[86:87], v2, v0
	v_or_b32_e32 v2, 7, v66
	v_or_b32_e32 v3, 6, v66
	v_cmp_le_i32_e64 s[76:77], v3, v0
	v_cmp_le_i32_e64 s[78:79], v2, v0
	v_or_b32_e32 v2, 17, v66
	v_or_b32_e32 v3, 16, v66
	v_cmp_le_i32_e64 s[68:69], v3, v0
	v_cmp_le_i32_e64 s[70:71], v2, v0
	v_or_b32_e32 v2, 19, v66
	v_or_b32_e32 v3, 18, v66
	v_cmp_le_i32_e64 s[60:61], v3, v0
	v_cmp_le_i32_e64 s[62:63], v2, v0
	v_or_b32_e32 v2, 21, v66
	v_or_b32_e32 v3, 20, v66
	v_pk_add_f32 v[16:17], v[64:65], 0 op_sel_hi:[1,0]
	v_pk_add_f32 v[14:15], v[62:63], 0 op_sel_hi:[1,0]
	v_pk_add_f32 v[12:13], v[60:61], 0 op_sel_hi:[1,0]
	v_pk_add_f32 v[10:11], v[58:59], 0 op_sel_hi:[1,0]
	v_pk_add_f32 v[8:9], v[56:57], 0 op_sel_hi:[1,0]
	v_pk_add_f32 v[6:7], v[54:55], 0 op_sel_hi:[1,0]
	v_pk_add_f32 v[4:5], v[52:53], 0 op_sel_hi:[1,0]
	v_cmp_le_i32_e64 s[50:51], v3, v0
	v_cmp_le_i32_e64 s[52:53], v2, v0
	v_pk_add_f32 v[2:3], v[50:51], 0 op_sel_hi:[1,0]
	v_or_b32_e32 v50, 23, v66
	v_or_b32_e32 v51, 22, v66
	v_cmp_gt_i32_e64 s[46:47], 0, v17
	v_cmp_gt_i32_e64 s[6:7], 0, v16
	v_cmp_le_i32_e64 s[8:9], v66, v0
	v_cmp_lt_i32_e64 s[4:5], v66, v0
	v_cmp_gt_i32_e64 s[90:91], 0, v14
	v_cmp_gt_i32_e64 s[96:97], 0, v15
	v_cmp_gt_i32_e64 s[82:83], 0, v12
	v_cmp_gt_i32_e64 s[88:89], 0, v13
	v_cmp_gt_i32_e64 s[74:75], 0, v10
	v_cmp_gt_i32_e64 s[80:81], 0, v11
	v_cmp_gt_i32_e64 s[66:67], 0, v8
	v_cmp_gt_i32_e64 s[72:73], 0, v9
	v_cmp_gt_i32_e64 s[58:59], 0, v6
	v_cmp_gt_i32_e64 s[64:65], 0, v7
	v_cmp_gt_i32_e64 s[48:49], 0, v4
	v_cmp_gt_i32_e64 s[56:57], 0, v5
	v_cmp_gt_i32_e64 s[0:1], 0, v2
	v_cmp_gt_i32_e64 s[44:45], 0, v3
	v_cmp_le_i32_e64 s[42:43], v51, v0
	s_andn2_b64 vcc, exec, s[40:41]
	v_cmp_le_i32_e64 s[54:55], v50, v0
	s_cbranch_vccnz .LBB0_402
	s_waitcnt vmcnt(0)
	v_mov_b64_e32 v[36:37], v[20:21]
	v_mov_b64_e32 v[40:41], v[24:25]
	v_mov_b64_e32 v[44:45], v[28:29]
	v_mov_b64_e32 v[48:49], v[32:33]
	v_mov_b64_e32 v[34:35], v[18:19]
	v_mov_b64_e32 v[38:39], v[22:23]
	v_mov_b64_e32 v[42:43], v[26:27]
	v_mov_b64_e32 v[46:47], v[30:31]

; #define MFMA32(a, b, c) __builtin_amdgcn_mfma_f32_32x32x16_bf16((a), (b), (c), 0, 0, 0)
; DI void a1_task(unsigned char* shm, const bf16_t* prm, const bf16_t* prt, unsigned* mask, int b, int qt, const int tid) {
;     ...
;             for (int hh = 0; hh < 8; ++hh) {
;                 bf16x8 qa[4];
; #pragma unroll
;                 for (int ks = 0; ks < 4; ++ks) qa[ks] = *(const bf16x8*)(qb0 + hh * 128 + 32 * ks);
;                 const float wv = wqs[hh * 32 + r];
;                 asm volatile("s_waitcnt lgkmcnt(0)" ::: "memory");
;                 f32x16 acc;
; #pragma unroll
;                 for (int i = 0; i < 16; ++i) acc[i] = 0.f;
; #pragma unroll
;                 for (int ks = 0; ks < 4; ++ks) acc = MFMA32(kf[ks], qa[ks], acc);
; #pragma unroll
;                 for (int i = 0; i < 16; ++i) idx[i] = fmaf(wv, fmaxf(acc[i], 0.f), idx[i]);
;             }
;     ...
;             if (hn) {
; #pragma unroll
;                 for (int ks = 0; ks < 4; ++ks) kf[ks] = kn[ks];
;             }
.LBB0_408:
	v_add_u32_e32 v95, s1, v118
	ds_read_b128 v[2:5], v95
	ds_read_b128 v[82:85], v95 offset:32
	ds_read_b128 v[86:89], v95 offset:64
	ds_read_b128 v[90:93], v95 offset:96
	v_add_u32_e32 v96, s1, v135
	s_waitcnt lgkmcnt(3)
	v_mfma_f32_32x32x16_bf16 v[2:17], v[34:37], v[2:5], 0
	ds_read_b32 v94, v96
	s_waitcnt lgkmcnt(0)
	s_addk_i32 s1, 0x100
	s_cmpk_lg_i32 s1, 0x400
	s_waitcnt lgkmcnt(3)
	v_mfma_f32_32x32x16_bf16 v[2:17], v[38:41], v[82:85], v[2:17]
	s_waitcnt lgkmcnt(2)
	v_mfma_f32_32x32x16_bf16 v[2:17], v[42:45], v[86:89], v[2:17]
	s_waitcnt lgkmcnt(1)
	v_mfma_f32_32x32x16_bf16 v[2:17], v[46:49], v[90:93], v[2:17]
	s_nop 11
	v_max_f32_e32 v2, 0, v2
	v_max_f32_e32 v3, 0, v3
	s_waitcnt lgkmcnt(0)
	v_pk_fma_f32 v[80:81], v[94:95], v[2:3], v[80:81] op_sel_hi:[0,1,1]
	v_max_f32_e32 v2, 0, v4
	v_max_f32_e32 v3, 0, v5
	v_pk_fma_f32 v[78:79], v[94:95], v[2:3], v[78:79] op_sel_hi:[0,1,1]
	v_max_f32_e32 v2, 0, v6
	v_max_f32_e32 v3, 0, v7
	v_pk_fma_f32 v[76:77], v[94:95], v[2:3], v[76:77] op_sel_hi:[0,1,1]
	v_max_f32_e32 v2, 0, v8
	v_max_f32_e32 v3, 0, v9
	v_pk_fma_f32 v[74:75], v[94:95], v[2:3], v[74:75] op_sel_hi:[0,1,1]
	v_max_f32_e32 v2, 0, v10
	v_max_f32_e32 v3, 0, v11
	v_pk_fma_f32 v[72:73], v[94:95], v[2:3], v[72:73] op_sel_hi:[0,1,1]
	v_max_f32_e32 v2, 0, v12
	v_max_f32_e32 v3, 0, v13
	v_pk_fma_f32 v[70:71], v[94:95], v[2:3], v[70:71] op_sel_hi:[0,1,1]
	v_max_f32_e32 v2, 0, v14
	v_max_f32_e32 v3, 0, v15
	v_pk_fma_f32 v[68:69], v[94:95], v[2:3], v[68:69] op_sel_hi:[0,1,1]
	v_max_f32_e32 v2, 0, v16
	v_max_f32_e32 v3, 0, v17
	v_pk_fma_f32 v[66:67], v[94:95], v[2:3], v[66:67] op_sel_hi:[0,1,1]
	ds_read_b128 v[2:5], v95 offset:128
	ds_read_b128 v[82:85], v95 offset:160
	ds_read_b128 v[86:89], v95 offset:192
	ds_read_b128 v[90:93], v95 offset:224
	ds_read_b32 v94, v96 offset:128
	s_waitcnt lgkmcnt(4)
	v_mfma_f32_32x32x16_bf16 v[2:17], v[34:37], v[2:5], 0
	s_waitcnt lgkmcnt(0)
	s_waitcnt lgkmcnt(3)
	v_mfma_f32_32x32x16_bf16 v[2:17], v[38:41], v[82:85], v[2:17]
	s_waitcnt lgkmcnt(2)
	v_mfma_f32_32x32x16_bf16 v[2:17], v[42:45], v[86:89], v[2:17]
	s_waitcnt lgkmcnt(1)
	v_mfma_f32_32x32x16_bf16 v[2:17], v[46:49], v[90:93], v[2:17]
	s_nop 11
	v_max_f32_e32 v2, 0, v2
	v_max_f32_e32 v3, 0, v3
	s_waitcnt lgkmcnt(0)
	v_pk_fma_f32 v[80:81], v[94:95], v[2:3], v[80:81] op_sel_hi:[0,1,1]
	v_max_f32_e32 v2, 0, v4
	v_max_f32_e32 v3, 0, v5
	v_pk_fma_f32 v[78:79], v[94:95], v[2:3], v[78:79] op_sel_hi:[0,1,1]
	v_max_f32_e32 v2, 0, v6
	v_max_f32_e32 v3, 0, v7
	v_pk_fma_f32 v[76:77], v[94:95], v[2:3], v[76:77] op_sel_hi:[0,1,1]
	v_max_f32_e32 v2, 0, v8
	v_max_f32_e32 v3, 0, v9
	v_pk_fma_f32 v[74:75], v[94:95], v[2:3], v[74:75] op_sel_hi:[0,1,1]
	v_max_f32_e32 v2, 0, v10
	v_max_f32_e32 v3, 0, v11
	v_pk_fma_f32 v[72:73], v[94:95], v[2:3], v[72:73] op_sel_hi:[0,1,1]
	v_max_f32_e32 v2, 0, v12
	v_max_f32_e32 v3, 0, v13
	v_pk_fma_f32 v[70:71], v[94:95], v[2:3], v[70:71] op_sel_hi:[0,1,1]
	v_max_f32_e32 v2, 0, v14
	v_max_f32_e32 v3, 0, v15
	v_pk_fma_f32 v[68:69], v[94:95], v[2:3], v[68:69] op_sel_hi:[0,1,1]
	v_max_f32_e32 v2, 0, v16
	v_max_f32_e32 v3, 0, v17
	v_pk_fma_f32 v[66:67], v[94:95], v[2:3], v[66:67] op_sel_hi:[0,1,1]
	s_cbranch_scc1 .LBB0_408
	v_or_b32_e32 v82, s0, v98
	v_or_b32_e32 v2, 3, v82
	v_or_b32_e32 v3, 2, v82
	v_cmp_le_i32_e64 s[92:93], v3, v0
	v_cmp_le_i32_e64 s[94:95], v2, v0
	v_or_b32_e32 v2, 5, v82
	v_or_b32_e32 v3, 4, v82
	v_cmp_le_i32_e64 s[84:85], v3, v0
	v_cmp_le_i32_e64 s[86:87], v2, v0
	v_or_b32_e32 v2, 7, v82
	v_or_b32_e32 v3, 6, v82
	v_cmp_le_i32_e64 s[76:77], v3, v0
	v_cmp_le_i32_e64 s[78:79], v2, v0
	v_or_b32_e32 v2, 17, v82
	v_or_b32_e32 v3, 16, v82
	v_cmp_le_i32_e64 s[68:69], v3, v0
	v_cmp_le_i32_e64 s[70:71], v2, v0
	v_or_b32_e32 v2, 19, v82
	v_or_b32_e32 v3, 18, v82
	v_cmp_le_i32_e64 s[60:61], v3, v0
	v_cmp_le_i32_e64 s[62:63], v2, v0
	v_or_b32_e32 v2, 21, v82
	v_or_b32_e32 v3, 20, v82
	v_cmp_le_i32_e64 s[52:53], v3, v0
	v_cmp_le_i32_e64 s[54:55], v2, v0
	v_pk_add_f32 v[2:3], v[66:67], 0 op_sel_hi:[1,0]
	v_or_b32_e32 v66, 23, v82
	v_or_b32_e32 v67, 22, v82
	v_pk_add_f32 v[16:17], v[80:81], 0 op_sel_hi:[1,0]
	v_cmp_le_i32_e64 s[8:9], v82, v0
	v_cmp_lt_i32_e64 s[4:5], v82, v0
	v_pk_add_f32 v[14:15], v[78:79], 0 op_sel_hi:[1,0]
	v_pk_add_f32 v[12:13], v[76:77], 0 op_sel_hi:[1,0]
	v_pk_add_f32 v[10:11], v[74:75], 0 op_sel_hi:[1,0]
	v_pk_add_f32 v[8:9], v[72:73], 0 op_sel_hi:[1,0]
	v_pk_add_f32 v[6:7], v[70:71], 0 op_sel_hi:[1,0]
	v_pk_add_f32 v[4:5], v[68:69], 0 op_sel_hi:[1,0]
	v_cmp_le_i32_e64 s[42:43], v67, v0
	v_cmp_le_i32_e64 s[44:45], v66, v0
	v_mov_b64_e32 v[68:69], v[36:37]
	v_mov_b64_e32 v[76:77], v[40:41]
	v_mov_b64_e32 v[84:85], v[44:45]
	v_mov_b64_e32 v[92:93], v[48:49]
	v_cmp_gt_i32_e64 s[96:97], 0, v17
	v_cmp_gt_i32_e64 s[6:7], 0, v16
	v_cmp_gt_i32_e64 s[90:91], 0, v14
	v_cmp_gt_i32_e64 s[46:47], 0, v15
	v_cmp_gt_i32_e64 s[82:83], 0, v12
	v_cmp_gt_i32_e64 s[88:89], 0, v13
	v_cmp_gt_i32_e64 s[74:75], 0, v10
	v_cmp_gt_i32_e64 s[80:81], 0, v11
	v_cmp_gt_i32_e64 s[66:67], 0, v8
	v_cmp_gt_i32_e64 s[72:73], 0, v9
	v_cmp_gt_i32_e64 s[58:59], 0, v6
	v_cmp_gt_i32_e64 s[64:65], 0, v7
	v_cmp_gt_i32_e64 s[50:51], 0, v4
	v_cmp_gt_i32_e64 s[56:57], 0, v5
	v_cmp_gt_i32_e64 s[0:1], 0, v2
	v_cmp_gt_i32_e64 s[48:49], 0, v3
	s_andn2_b64 vcc, exec, s[40:41]
	v_mov_b64_e32 v[66:67], v[34:35]
	v_mov_b64_e32 v[74:75], v[38:39]
	v_mov_b64_e32 v[82:83], v[42:43]
	v_mov_b64_e32 v[90:91], v[46:47]
	s_cbranch_vccnz .LBB0_411
	s_waitcnt vmcnt(3)
	v_mov_b64_e32 v[68:69], v[52:53]
	s_waitcnt vmcnt(2)
	v_mov_b64_e32 v[76:77], v[56:57]
	s_waitcnt vmcnt(1)
	v_mov_b64_e32 v[84:85], v[60:61]
	s_waitcnt vmcnt(0)
	v_mov_b64_e32 v[92:93], v[64:65]
	v_mov_b64_e32 v[66:67], v[50:51]
	v_mov_b64_e32 v[74:75], v[54:55]
	v_mov_b64_e32 v[82:83], v[58:59]
	v_mov_b64_e32 v[90:91], v[62:63]

; #define MFMA32(a, b, c) __builtin_amdgcn_mfma_f32_32x32x16_bf16((a), (b), (c), 0, 0, 0)
; DI void a1_task(unsigned char* shm, const bf16_t* prm, const bf16_t* prt, unsigned* mask, int b, int qt, const int tid) {
;     ...
;             for (int hh = 0; hh < 8; ++hh) {
;                 bf16x8 qa[4];
; #pragma unroll
;                 for (int ks = 0; ks < 4; ++ks) qa[ks] = *(const bf16x8*)(qb0 + hh * 128 + 32 * ks);
;                 const float wv = wqs[hh * 32 + r];
;                 asm volatile("s_waitcnt lgkmcnt(0)" ::: "memory");
;                 f32x16 acc;
; #pragma unroll
;                 for (int i = 0; i < 16; ++i) acc[i] = 0.f;
; #pragma unroll
;                 for (int ks = 0; ks < 4; ++ks) acc = MFMA32(kf[ks], qa[ks], acc);
; #pragma unroll
;                 for (int i = 0; i < 16; ++i) idx[i] = fmaf(wv, fmaxf(acc[i], 0.f), idx[i]);
;             }
;     ...
;             if (hn) {
; #pragma unroll
;                 for (int ks = 0; ks < 4; ++ks) kf[ks] = kn[ks];
;             }
.LBB0_418:
	v_add_u32_e32 v95, s1, v118
	ds_read_b128 v[2:5], v95
	ds_read_b128 v[70:73], v95 offset:32
	ds_read_b128 v[78:81], v95 offset:64
	ds_read_b128 v[86:89], v95 offset:96
	v_add_u32_e32 v96, s1, v135
	s_waitcnt lgkmcnt(3)
	v_mfma_f32_32x32x16_bf16 v[2:17], v[66:69], v[2:5], 0
	ds_read_b32 v94, v96
	s_waitcnt lgkmcnt(0)
	s_addk_i32 s1, 0x100
	s_cmpk_lg_i32 s1, 0x400
	s_waitcnt lgkmcnt(3)
	v_mfma_f32_32x32x16_bf16 v[2:17], v[74:77], v[70:73], v[2:17]
	s_waitcnt lgkmcnt(2)
	v_mfma_f32_32x32x16_bf16 v[2:17], v[82:85], v[78:81], v[2:17]
	s_waitcnt lgkmcnt(1)
	v_mfma_f32_32x32x16_bf16 v[2:17], v[90:93], v[86:89], v[2:17]
	s_nop 11
	v_max_f32_e32 v2, 0, v2
	v_max_f32_e32 v3, 0, v3
	s_waitcnt lgkmcnt(0)
	v_pk_fma_f32 v[32:33], v[94:95], v[2:3], v[32:33] op_sel_hi:[0,1,1]
	v_max_f32_e32 v2, 0, v4
	v_max_f32_e32 v3, 0, v5
	v_pk_fma_f32 v[30:31], v[94:95], v[2:3], v[30:31] op_sel_hi:[0,1,1]
	v_max_f32_e32 v2, 0, v6
	v_max_f32_e32 v3, 0, v7
	v_pk_fma_f32 v[28:29], v[94:95], v[2:3], v[28:29] op_sel_hi:[0,1,1]
	v_max_f32_e32 v2, 0, v8
	v_max_f32_e32 v3, 0, v9
	v_pk_fma_f32 v[26:27], v[94:95], v[2:3], v[26:27] op_sel_hi:[0,1,1]
	v_max_f32_e32 v2, 0, v10
	v_max_f32_e32 v3, 0, v11
	v_pk_fma_f32 v[24:25], v[94:95], v[2:3], v[24:25] op_sel_hi:[0,1,1]
	v_max_f32_e32 v2, 0, v12
	v_max_f32_e32 v3, 0, v13
	v_pk_fma_f32 v[22:23], v[94:95], v[2:3], v[22:23] op_sel_hi:[0,1,1]
	v_max_f32_e32 v2, 0, v14
	v_max_f32_e32 v3, 0, v15
	v_pk_fma_f32 v[20:21], v[94:95], v[2:3], v[20:21] op_sel_hi:[0,1,1]
	v_max_f32_e32 v2, 0, v16
	v_max_f32_e32 v3, 0, v17
	v_pk_fma_f32 v[18:19], v[94:95], v[2:3], v[18:19] op_sel_hi:[0,1,1]
	ds_read_b128 v[2:5], v95 offset:128
	ds_read_b128 v[70:73], v95 offset:160
	ds_read_b128 v[78:81], v95 offset:192
	ds_read_b128 v[86:89], v95 offset:224
	ds_read_b32 v94, v96 offset:128
	s_waitcnt lgkmcnt(4)
	v_mfma_f32_32x32x16_bf16 v[2:17], v[66:69], v[2:5], 0
	s_waitcnt lgkmcnt(0)
	s_waitcnt lgkmcnt(3)
	v_mfma_f32_32x32x16_bf16 v[2:17], v[74:77], v[70:73], v[2:17]
	s_waitcnt lgkmcnt(2)
	v_mfma_f32_32x32x16_bf16 v[2:17], v[82:85], v[78:81], v[2:17]
	s_waitcnt lgkmcnt(1)
	v_mfma_f32_32x32x16_bf16 v[2:17], v[90:93], v[86:89], v[2:17]
	s_nop 11
	v_max_f32_e32 v2, 0, v2
	v_max_f32_e32 v3, 0, v3
	s_waitcnt lgkmcnt(0)
	v_pk_fma_f32 v[32:33], v[94:95], v[2:3], v[32:33] op_sel_hi:[0,1,1]
	v_max_f32_e32 v2, 0, v4
	v_max_f32_e32 v3, 0, v5
	v_pk_fma_f32 v[30:31], v[94:95], v[2:3], v[30:31] op_sel_hi:[0,1,1]
	v_max_f32_e32 v2, 0, v6
	v_max_f32_e32 v3, 0, v7
	v_pk_fma_f32 v[28:29], v[94:95], v[2:3], v[28:29] op_sel_hi:[0,1,1]
	v_max_f32_e32 v2, 0, v8
	v_max_f32_e32 v3, 0, v9
	v_pk_fma_f32 v[26:27], v[94:95], v[2:3], v[26:27] op_sel_hi:[0,1,1]
	v_max_f32_e32 v2, 0, v10
	v_max_f32_e32 v3, 0, v11
	v_pk_fma_f32 v[24:25], v[94:95], v[2:3], v[24:25] op_sel_hi:[0,1,1]
	v_max_f32_e32 v2, 0, v12
	v_max_f32_e32 v3, 0, v13
	v_pk_fma_f32 v[22:23], v[94:95], v[2:3], v[22:23] op_sel_hi:[0,1,1]
	v_max_f32_e32 v2, 0, v14
	v_max_f32_e32 v3, 0, v15
	v_pk_fma_f32 v[20:21], v[94:95], v[2:3], v[20:21] op_sel_hi:[0,1,1]
	v_max_f32_e32 v2, 0, v16
	v_max_f32_e32 v3, 0, v17
	v_pk_fma_f32 v[18:19], v[94:95], v[2:3], v[18:19] op_sel_hi:[0,1,1]
	s_cbranch_scc1 .LBB0_418
	v_or_b32_e32 v70, s0, v98
	v_or_b32_e32 v2, 3, v70
	v_or_b32_e32 v3, 2, v70
	v_cmp_le_i32_e64 s[92:93], v3, v0
	v_cmp_le_i32_e64 s[94:95], v2, v0
	v_or_b32_e32 v2, 5, v70
	v_or_b32_e32 v3, 4, v70
	v_cmp_le_i32_e64 s[84:85], v3, v0
	v_cmp_le_i32_e64 s[86:87], v2, v0
	v_or_b32_e32 v2, 7, v70
	v_or_b32_e32 v3, 6, v70
	v_cmp_le_i32_e64 s[76:77], v3, v0
	v_cmp_le_i32_e64 s[78:79], v2, v0
	v_or_b32_e32 v2, 17, v70
	v_or_b32_e32 v3, 16, v70
	v_cmp_le_i32_e64 s[68:69], v3, v0
	v_cmp_le_i32_e64 s[70:71], v2, v0
	v_or_b32_e32 v2, 19, v70
	v_or_b32_e32 v3, 18, v70
	v_cmp_le_i32_e64 s[60:61], v3, v0
	v_cmp_le_i32_e64 s[62:63], v2, v0
	v_or_b32_e32 v2, 21, v70
	v_or_b32_e32 v3, 20, v70
	v_pk_add_f32 v[16:17], v[32:33], 0 op_sel_hi:[1,0]
	v_cmp_le_i32_e64 s[8:9], v70, v0
	v_cmp_lt_i32_e64 s[4:5], v70, v0
	v_pk_add_f32 v[14:15], v[30:31], 0 op_sel_hi:[1,0]
	v_pk_add_f32 v[12:13], v[28:29], 0 op_sel_hi:[1,0]
	v_pk_add_f32 v[10:11], v[26:27], 0 op_sel_hi:[1,0]
	v_pk_add_f32 v[8:9], v[24:25], 0 op_sel_hi:[1,0]
	v_pk_add_f32 v[6:7], v[22:23], 0 op_sel_hi:[1,0]
	v_pk_add_f32 v[4:5], v[20:21], 0 op_sel_hi:[1,0]
	v_cmp_le_i32_e64 s[52:53], v3, v0
	v_cmp_le_i32_e64 s[54:55], v2, v0
	v_pk_add_f32 v[2:3], v[18:19], 0 op_sel_hi:[1,0]
	v_or_b32_e32 v18, 23, v70
	v_or_b32_e32 v19, 22, v70
	v_mov_b64_e32 v[72:73], v[68:69]
	v_mov_b64_e32 v[80:81], v[76:77]
	v_mov_b64_e32 v[88:89], v[84:85]
	v_mov_b64_e32 v[96:97], v[92:93]
	v_cmp_gt_i32_e64 s[96:97], 0, v17
	v_cmp_gt_i32_e64 s[6:7], 0, v16
	v_cmp_gt_i32_e64 s[90:91], 0, v14
	v_cmp_gt_i32_e64 s[46:47], 0, v15
	v_cmp_gt_i32_e64 s[82:83], 0, v12
	v_cmp_gt_i32_e64 s[88:89], 0, v13
	v_cmp_gt_i32_e64 s[74:75], 0, v10
	v_cmp_gt_i32_e64 s[80:81], 0, v11
	v_cmp_gt_i32_e64 s[66:67], 0, v8
	v_cmp_gt_i32_e64 s[72:73], 0, v9
	v_cmp_gt_i32_e64 s[58:59], 0, v6
	v_cmp_gt_i32_e64 s[64:65], 0, v7
	v_cmp_gt_i32_e64 s[50:51], 0, v4
	v_cmp_gt_i32_e64 s[56:57], 0, v5
	v_cmp_gt_i32_e64 s[0:1], 0, v2
	v_cmp_gt_i32_e64 s[48:49], 0, v3
	v_cmp_le_i32_e64 s[42:43], v19, v0
	v_cmp_le_i32_e64 s[44:45], v18, v0
	s_andn2_b64 vcc, exec, s[40:41]
	v_mov_b64_e32 v[70:71], v[66:67]
	v_mov_b64_e32 v[78:79], v[74:75]
	v_mov_b64_e32 v[86:87], v[82:83]
	v_mov_b64_e32 v[94:95], v[90:91]
	s_cbranch_vccnz .LBB0_421
	s_waitcnt vmcnt(3)
	v_mov_b64_e32 v[72:73], v[36:37]
	s_waitcnt vmcnt(2)
	v_mov_b64_e32 v[80:81], v[40:41]
	s_waitcnt vmcnt(1)
	v_mov_b64_e32 v[88:89], v[44:45]
	s_waitcnt vmcnt(0)
	v_mov_b64_e32 v[96:97], v[48:49]
	v_mov_b64_e32 v[70:71], v[34:35]
	v_mov_b64_e32 v[78:79], v[38:39]
	v_mov_b64_e32 v[86:87], v[42:43]
	v_mov_b64_e32 v[94:95], v[46:47]

; #define MFMA32(a, b, c) __builtin_amdgcn_mfma_f32_32x32x16_bf16((a), (b), (c), 0, 0, 0)
; DI void a1_task(unsigned char* shm, const bf16_t* prm, const bf16_t* prt, unsigned* mask, int b, int qt, const int tid) {
;     ...
;             for (int hh = 0; hh < 8; ++hh) {
;                 bf16x8 qa[4];
; #pragma unroll
;                 for (int ks = 0; ks < 4; ++ks) qa[ks] = *(const bf16x8*)(qb0 + hh * 128 + 32 * ks);
;                 const float wv = wqs[hh * 32 + r];
;                 asm volatile("s_waitcnt lgkmcnt(0)" ::: "memory");
;                 f32x16 acc;
; #pragma unroll
;                 for (int i = 0; i < 16; ++i) acc[i] = 0.f;
; #pragma unroll
;                 for (int ks = 0; ks < 4; ++ks) acc = MFMA32(kf[ks], qa[ks], acc);
; #pragma unroll
;                 for (int i = 0; i < 16; ++i) idx[i] = fmaf(wv, fmaxf(acc[i], 0.f), idx[i]);
;             }
; #pragma unroll
;             for (int i = 0; i < 16; ++i) {
;                 const int s = s0 + 16 * (i >> 3) + 8 * h + (i & 7);
;                 const unsigned u = __float_as_uint(idx[i] + 0.0f);
;                 const unsigned k = (u & 0x80000000u) ? ~u : (u | 0x80000000u);
;                 key[jt][i] = (s <= t0 + r) ? k : 0u;
;             }
;             if (hn) {
; #pragma unroll
;                 for (int ks = 0; ks < 4; ++ks) kf[ks] = kn[ks];
.LBB0_428:
	v_add_u32_e32 v91, s1, v118
	ds_read_b128 v[2:5], v91
	ds_read_b128 v[66:69], v91 offset:32
	ds_read_b128 v[74:77], v91 offset:64
	ds_read_b128 v[82:85], v91 offset:96
	v_add_u32_e32 v92, s1, v135
	s_waitcnt lgkmcnt(3)
	v_mfma_f32_32x32x16_bf16 v[2:17], v[70:73], v[2:5], 0
	ds_read_b32 v90, v92
	s_waitcnt lgkmcnt(0)
	s_addk_i32 s1, 0x100
	s_cmpk_lg_i32 s1, 0x400
	s_waitcnt lgkmcnt(3)
	v_mfma_f32_32x32x16_bf16 v[2:17], v[78:81], v[66:69], v[2:17]
	s_waitcnt lgkmcnt(2)
	v_mfma_f32_32x32x16_bf16 v[2:17], v[86:89], v[74:77], v[2:17]
	s_waitcnt lgkmcnt(1)
	v_mfma_f32_32x32x16_bf16 v[2:17], v[94:97], v[82:85], v[2:17]
	s_nop 11
	v_max_f32_e32 v2, 0, v2
	v_max_f32_e32 v3, 0, v3
	s_waitcnt lgkmcnt(0)
	v_pk_fma_f32 v[64:65], v[90:91], v[2:3], v[64:65] op_sel_hi:[0,1,1]
	v_max_f32_e32 v2, 0, v4
	v_max_f32_e32 v3, 0, v5
	v_pk_fma_f32 v[62:63], v[90:91], v[2:3], v[62:63] op_sel_hi:[0,1,1]
	v_max_f32_e32 v2, 0, v6
	v_max_f32_e32 v3, 0, v7
	v_pk_fma_f32 v[60:61], v[90:91], v[2:3], v[60:61] op_sel_hi:[0,1,1]
	v_max_f32_e32 v2, 0, v8
	v_max_f32_e32 v3, 0, v9
	v_pk_fma_f32 v[58:59], v[90:91], v[2:3], v[58:59] op_sel_hi:[0,1,1]
	v_max_f32_e32 v2, 0, v10
	v_max_f32_e32 v3, 0, v11
	v_pk_fma_f32 v[56:57], v[90:91], v[2:3], v[56:57] op_sel_hi:[0,1,1]
	v_max_f32_e32 v2, 0, v12
	v_max_f32_e32 v3, 0, v13
	v_pk_fma_f32 v[54:55], v[90:91], v[2:3], v[54:55] op_sel_hi:[0,1,1]
	v_max_f32_e32 v2, 0, v14
	v_max_f32_e32 v3, 0, v15
	v_pk_fma_f32 v[52:53], v[90:91], v[2:3], v[52:53] op_sel_hi:[0,1,1]
	v_max_f32_e32 v2, 0, v16
	v_max_f32_e32 v3, 0, v17
	v_pk_fma_f32 v[50:51], v[90:91], v[2:3], v[50:51] op_sel_hi:[0,1,1]
	ds_read_b128 v[2:5], v91 offset:128
	ds_read_b128 v[66:69], v91 offset:160
	ds_read_b128 v[74:77], v91 offset:192
	ds_read_b128 v[82:85], v91 offset:224
	ds_read_b32 v90, v92 offset:128
	s_waitcnt lgkmcnt(4)
	v_mfma_f32_32x32x16_bf16 v[2:17], v[70:73], v[2:5], 0
	s_waitcnt lgkmcnt(0)
	s_waitcnt lgkmcnt(3)
	v_mfma_f32_32x32x16_bf16 v[2:17], v[78:81], v[66:69], v[2:17]
	s_waitcnt lgkmcnt(2)
	v_mfma_f32_32x32x16_bf16 v[2:17], v[86:89], v[74:77], v[2:17]
	s_waitcnt lgkmcnt(1)
	v_mfma_f32_32x32x16_bf16 v[2:17], v[94:97], v[82:85], v[2:17]
	s_nop 11
	v_max_f32_e32 v2, 0, v2
	v_max_f32_e32 v3, 0, v3
	s_waitcnt lgkmcnt(0)
	v_pk_fma_f32 v[64:65], v[90:91], v[2:3], v[64:65] op_sel_hi:[0,1,1]
	v_max_f32_e32 v2, 0, v4
	v_max_f32_e32 v3, 0, v5
	v_pk_fma_f32 v[62:63], v[90:91], v[2:3], v[62:63] op_sel_hi:[0,1,1]
	v_max_f32_e32 v2, 0, v6
	v_max_f32_e32 v3, 0, v7
	v_pk_fma_f32 v[60:61], v[90:91], v[2:3], v[60:61] op_sel_hi:[0,1,1]
	v_max_f32_e32 v2, 0, v8
	v_max_f32_e32 v3, 0, v9
	v_pk_fma_f32 v[58:59], v[90:91], v[2:3], v[58:59] op_sel_hi:[0,1,1]
	v_max_f32_e32 v2, 0, v10
	v_max_f32_e32 v3, 0, v11
	v_pk_fma_f32 v[56:57], v[90:91], v[2:3], v[56:57] op_sel_hi:[0,1,1]
	v_max_f32_e32 v2, 0, v12
	v_max_f32_e32 v3, 0, v13
	v_pk_fma_f32 v[54:55], v[90:91], v[2:3], v[54:55] op_sel_hi:[0,1,1]
	v_max_f32_e32 v2, 0, v14
	v_max_f32_e32 v3, 0, v15
	v_pk_fma_f32 v[52:53], v[90:91], v[2:3], v[52:53] op_sel_hi:[0,1,1]
	v_max_f32_e32 v2, 0, v16
	v_max_f32_e32 v3, 0, v17
	v_pk_fma_f32 v[50:51], v[90:91], v[2:3], v[50:51] op_sel_hi:[0,1,1]
	s_cbranch_scc1 .LBB0_428
	v_or_b32_e32 v66, s0, v98
	v_or_b32_e32 v2, 3, v66
	v_or_b32_e32 v3, 2, v66
	v_cmp_le_i32_e64 s[92:93], v3, v0
	v_cmp_le_i32_e64 s[94:95], v2, v0
	v_or_b32_e32 v2, 5, v66
	v_or_b32_e32 v3, 4, v66
	v_cmp_le_i32_e64 s[84:85], v3, v0
	v_cmp_le_i32_e64 s[86:87], v2, v0
	v_or_b32_e32 v2, 7, v66
	v_or_b32_e32 v3, 6, v66
	v_cmp_le_i32_e64 s[76:77], v3, v0
	v_cmp_le_i32_e64 s[78:79], v2, v0
	v_or_b32_e32 v2, 17, v66
	v_or_b32_e32 v3, 16, v66
	v_cmp_le_i32_e64 s[68:69], v3, v0
	v_cmp_le_i32_e64 s[70:71], v2, v0
	v_or_b32_e32 v2, 19, v66
	v_or_b32_e32 v3, 18, v66
	v_cmp_le_i32_e64 s[60:61], v3, v0
	v_cmp_le_i32_e64 s[62:63], v2, v0
	v_or_b32_e32 v2, 21, v66
	v_or_b32_e32 v3, 20, v66
	v_cmp_le_i32_e64 s[52:53], v3, v0
	v_cmp_le_i32_e64 s[54:55], v2, v0
	v_pk_add_f32 v[2:3], v[50:51], 0 op_sel_hi:[1,0]
	v_or_b32_e32 v50, 23, v66
	v_or_b32_e32 v51, 22, v66
	v_pk_add_f32 v[16:17], v[64:65], 0 op_sel_hi:[1,0]
	v_pk_add_f32 v[14:15], v[62:63], 0 op_sel_hi:[1,0]
	v_pk_add_f32 v[12:13], v[60:61], 0 op_sel_hi:[1,0]
	v_pk_add_f32 v[10:11], v[58:59], 0 op_sel_hi:[1,0]
	v_pk_add_f32 v[8:9], v[56:57], 0 op_sel_hi:[1,0]
	v_pk_add_f32 v[6:7], v[54:55], 0 op_sel_hi:[1,0]
	v_pk_add_f32 v[4:5], v[52:53], 0 op_sel_hi:[1,0]
	v_cmp_le_i32_e64 s[42:43], v51, v0
	v_cmp_le_i32_e64 s[44:45], v50, v0
	v_mov_b64_e32 v[50:51], v[70:71]
	v_mov_b64_e32 v[54:55], v[78:79]
	v_mov_b64_e32 v[58:59], v[86:87]
	v_mov_b64_e32 v[62:63], v[94:95]
	v_cmp_gt_i32_e64 s[96:97], 0, v17
	v_cmp_gt_i32_e64 s[6:7], 0, v16
	v_cmp_le_i32_e64 s[8:9], v66, v0
	v_cmp_lt_i32_e64 s[4:5], v66, v0
	v_cmp_gt_i32_e64 s[90:91], 0, v14
	v_cmp_gt_i32_e64 s[46:47], 0, v15
	v_cmp_gt_i32_e64 s[82:83], 0, v12
	v_cmp_gt_i32_e64 s[88:89], 0, v13
	v_cmp_gt_i32_e64 s[74:75], 0, v10
	v_cmp_gt_i32_e64 s[80:81], 0, v11
	v_cmp_gt_i32_e64 s[66:67], 0, v8
	v_cmp_gt_i32_e64 s[72:73], 0, v9
	v_cmp_gt_i32_e64 s[58:59], 0, v6
	v_cmp_gt_i32_e64 s[64:65], 0, v7
	v_cmp_gt_i32_e64 s[50:51], 0, v4
	v_cmp_gt_i32_e64 s[56:57], 0, v5
	v_cmp_gt_i32_e64 s[0:1], 0, v2
	v_cmp_gt_i32_e64 s[48:49], 0, v3
	s_andn2_b64 vcc, exec, s[40:41]
	v_mov_b64_e32 v[52:53], v[72:73]
	v_mov_b64_e32 v[56:57], v[80:81]
	v_mov_b64_e32 v[60:61], v[88:89]
	v_mov_b64_e32 v[64:65], v[96:97]
	s_cbranch_vccnz .LBB0_431
	s_waitcnt vmcnt(3)
	v_mov_b64_e32 v[52:53], v[20:21]
	s_waitcnt vmcnt(2)
	v_mov_b64_e32 v[56:57], v[24:25]
	s_waitcnt vmcnt(1)
	v_mov_b64_e32 v[60:61], v[28:29]
	s_waitcnt vmcnt(0)
	v_mov_b64_e32 v[64:65], v[32:33]
	v_mov_b64_e32 v[50:51], v[18:19]
	v_mov_b64_e32 v[54:55], v[22:23]
	v_mov_b64_e32 v[58:59], v[26:27]
	v_mov_b64_e32 v[62:63], v[30:31]

; #define MFMA32(a, b, c) __builtin_amdgcn_mfma_f32_32x32x16_bf16((a), (b), (c), 0, 0, 0)
; DI void a1_task(unsigned char* shm, const bf16_t* prm, const bf16_t* prt, unsigned* mask, int b, int qt, const int tid) {
;     ...
;             for (int hh = 0; hh < 8; ++hh) {
;                 bf16x8 qa[4];
; #pragma unroll
;                 for (int ks = 0; ks < 4; ++ks) qa[ks] = *(const bf16x8*)(qb0 + hh * 128 + 32 * ks);
;                 const float wv = wqs[hh * 32 + r];
;                 asm volatile("s_waitcnt lgkmcnt(0)" ::: "memory");
;                 f32x16 acc;
; #pragma unroll
;                 for (int i = 0; i < 16; ++i) acc[i] = 0.f;
; #pragma unroll
;                 for (int ks = 0; ks < 4; ++ks) acc = MFMA32(kf[ks], qa[ks], acc);
; #pragma unroll
;                 for (int i = 0; i < 16; ++i) idx[i] = fmaf(wv, fmaxf(acc[i], 0.f), idx[i]);
;             }
; #pragma unroll
;             for (int i = 0; i < 16; ++i) {
;                 const int s = s0 + 16 * (i >> 3) + 8 * h + (i & 7);
;                 const unsigned u = __float_as_uint(idx[i] + 0.0f);
;                 const unsigned k = (u & 0x80000000u) ? ~u : (u | 0x80000000u);
;                 key[jt][i] = (s <= t0 + r) ? k : 0u;
;             }
;             if (hn) {
; #pragma unroll
;                 for (int ks = 0; ks < 4; ++ks) kf[ks] = kn[ks];
.LBB0_438:
	v_add_u32_e32 v199, s1, v118
	ds_read_b128 v[2:5], v199
	ds_read_b128 v[86:89], v199 offset:32
	ds_read_b128 v[94:97], v199 offset:64
	ds_read_b128 v[244:247], v199 offset:96
	v_add_u32_e32 v200, s1, v135
	s_waitcnt lgkmcnt(3)
	v_mfma_f32_32x32x16_bf16 v[2:17], v[50:53], v[2:5], 0
	ds_read_b32 v198, v200
	s_waitcnt lgkmcnt(0)
	s_addk_i32 s1, 0x100
	s_cmpk_lg_i32 s1, 0x400
	s_waitcnt lgkmcnt(3)
	v_mfma_f32_32x32x16_bf16 v[2:17], v[54:57], v[86:89], v[2:17]
	s_waitcnt lgkmcnt(2)
	v_mfma_f32_32x32x16_bf16 v[2:17], v[58:61], v[94:97], v[2:17]
	s_waitcnt lgkmcnt(1)
	v_mfma_f32_32x32x16_bf16 v[2:17], v[62:65], v[244:247], v[2:17]
	s_nop 11
	v_max_f32_e32 v2, 0, v2
	v_max_f32_e32 v3, 0, v3
	s_waitcnt lgkmcnt(0)
	v_pk_fma_f32 v[80:81], v[198:199], v[2:3], v[80:81] op_sel_hi:[0,1,1]
	v_max_f32_e32 v2, 0, v4
	v_max_f32_e32 v3, 0, v5
	v_pk_fma_f32 v[78:79], v[198:199], v[2:3], v[78:79] op_sel_hi:[0,1,1]
	v_max_f32_e32 v2, 0, v6
	v_max_f32_e32 v3, 0, v7
	v_pk_fma_f32 v[76:77], v[198:199], v[2:3], v[76:77] op_sel_hi:[0,1,1]
	v_max_f32_e32 v2, 0, v8
	v_max_f32_e32 v3, 0, v9
	v_pk_fma_f32 v[74:75], v[198:199], v[2:3], v[74:75] op_sel_hi:[0,1,1]
	v_max_f32_e32 v2, 0, v10
	v_max_f32_e32 v3, 0, v11
	v_pk_fma_f32 v[72:73], v[198:199], v[2:3], v[72:73] op_sel_hi:[0,1,1]
	v_max_f32_e32 v2, 0, v12
	v_max_f32_e32 v3, 0, v13
	v_pk_fma_f32 v[70:71], v[198:199], v[2:3], v[70:71] op_sel_hi:[0,1,1]
	v_max_f32_e32 v2, 0, v14
	v_max_f32_e32 v3, 0, v15
	v_pk_fma_f32 v[68:69], v[198:199], v[2:3], v[68:69] op_sel_hi:[0,1,1]
	v_max_f32_e32 v2, 0, v16
	v_max_f32_e32 v3, 0, v17
	v_pk_fma_f32 v[66:67], v[198:199], v[2:3], v[66:67] op_sel_hi:[0,1,1]
	ds_read_b128 v[2:5], v199 offset:128
	ds_read_b128 v[86:89], v199 offset:160
	ds_read_b128 v[94:97], v199 offset:192
	ds_read_b128 v[244:247], v199 offset:224
	ds_read_b32 v198, v200 offset:128
	s_waitcnt lgkmcnt(4)
	v_mfma_f32_32x32x16_bf16 v[2:17], v[50:53], v[2:5], 0
	s_waitcnt lgkmcnt(0)
	s_waitcnt lgkmcnt(3)
	v_mfma_f32_32x32x16_bf16 v[2:17], v[54:57], v[86:89], v[2:17]
	s_waitcnt lgkmcnt(2)
	v_mfma_f32_32x32x16_bf16 v[2:17], v[58:61], v[94:97], v[2:17]
	s_waitcnt lgkmcnt(1)
	v_mfma_f32_32x32x16_bf16 v[2:17], v[62:65], v[244:247], v[2:17]
	s_nop 11
	v_max_f32_e32 v2, 0, v2
	v_max_f32_e32 v3, 0, v3
	s_waitcnt lgkmcnt(0)
	v_pk_fma_f32 v[80:81], v[198:199], v[2:3], v[80:81] op_sel_hi:[0,1,1]
	v_max_f32_e32 v2, 0, v4
	v_max_f32_e32 v3, 0, v5
	v_pk_fma_f32 v[78:79], v[198:199], v[2:3], v[78:79] op_sel_hi:[0,1,1]
	v_max_f32_e32 v2, 0, v6
	v_max_f32_e32 v3, 0, v7
	v_pk_fma_f32 v[76:77], v[198:199], v[2:3], v[76:77] op_sel_hi:[0,1,1]
	v_max_f32_e32 v2, 0, v8
	v_max_f32_e32 v3, 0, v9
	v_pk_fma_f32 v[74:75], v[198:199], v[2:3], v[74:75] op_sel_hi:[0,1,1]
	v_max_f32_e32 v2, 0, v10
	v_max_f32_e32 v3, 0, v11
	v_pk_fma_f32 v[72:73], v[198:199], v[2:3], v[72:73] op_sel_hi:[0,1,1]
	v_max_f32_e32 v2, 0, v12
	v_max_f32_e32 v3, 0, v13
	v_pk_fma_f32 v[70:71], v[198:199], v[2:3], v[70:71] op_sel_hi:[0,1,1]
	v_max_f32_e32 v2, 0, v14
	v_max_f32_e32 v3, 0, v15
	v_pk_fma_f32 v[68:69], v[198:199], v[2:3], v[68:69] op_sel_hi:[0,1,1]
	v_max_f32_e32 v2, 0, v16
	v_max_f32_e32 v3, 0, v17
	v_pk_fma_f32 v[66:67], v[198:199], v[2:3], v[66:67] op_sel_hi:[0,1,1]
	s_cbranch_scc1 .LBB0_438
	v_or_b32_e32 v86, s0, v98
	v_or_b32_e32 v2, 3, v86
	v_or_b32_e32 v3, 2, v86
	v_cmp_le_i32_e64 s[92:93], v3, v0
	v_cmp_le_i32_e64 s[94:95], v2, v0
	v_or_b32_e32 v2, 5, v86
	v_or_b32_e32 v3, 4, v86
	v_cmp_le_i32_e64 s[84:85], v3, v0
	v_cmp_le_i32_e64 s[86:87], v2, v0
	v_or_b32_e32 v2, 7, v86
	v_or_b32_e32 v3, 6, v86
	v_cmp_le_i32_e64 s[76:77], v3, v0
	v_cmp_le_i32_e64 s[78:79], v2, v0
	v_or_b32_e32 v2, 17, v86
	v_or_b32_e32 v3, 16, v86
	v_cmp_le_i32_e64 s[68:69], v3, v0
	v_cmp_le_i32_e64 s[70:71], v2, v0
	v_or_b32_e32 v2, 19, v86
	v_or_b32_e32 v3, 18, v86
	v_cmp_le_i32_e64 s[60:61], v3, v0
	v_cmp_le_i32_e64 s[62:63], v2, v0
	v_or_b32_e32 v2, 21, v86
	v_or_b32_e32 v3, 20, v86
	v_cmp_le_i32_e64 s[52:53], v3, v0
	v_cmp_le_i32_e64 s[54:55], v2, v0
	v_pk_add_f32 v[2:3], v[66:67], 0 op_sel_hi:[1,0]
	v_or_b32_e32 v66, 23, v86
	v_or_b32_e32 v67, 22, v86
	v_pk_add_f32 v[16:17], v[80:81], 0 op_sel_hi:[1,0]
	v_pk_add_f32 v[14:15], v[78:79], 0 op_sel_hi:[1,0]
	v_pk_add_f32 v[12:13], v[76:77], 0 op_sel_hi:[1,0]
	v_pk_add_f32 v[10:11], v[74:75], 0 op_sel_hi:[1,0]
	v_pk_add_f32 v[8:9], v[72:73], 0 op_sel_hi:[1,0]
	v_pk_add_f32 v[6:7], v[70:71], 0 op_sel_hi:[1,0]
	v_pk_add_f32 v[4:5], v[68:69], 0 op_sel_hi:[1,0]
	v_cmp_le_i32_e64 s[42:43], v67, v0
	v_cmp_le_i32_e64 s[44:45], v66, v0
	v_mov_b64_e32 v[68:69], v[52:53]
	v_mov_b64_e32 v[72:73], v[56:57]
	v_mov_b64_e32 v[76:77], v[60:61]
	v_mov_b64_e32 v[80:81], v[64:65]
	v_cmp_gt_i32_e64 s[96:97], 0, v17
	v_cmp_gt_i32_e64 s[6:7], 0, v16
	v_cmp_le_i32_e64 s[8:9], v86, v0
	v_cmp_lt_i32_e64 s[4:5], v86, v0
	v_cmp_gt_i32_e64 s[90:91], 0, v14
	v_cmp_gt_i32_e64 s[46:47], 0, v15
	v_cmp_gt_i32_e64 s[82:83], 0, v12
	v_cmp_gt_i32_e64 s[88:89], 0, v13
	v_cmp_gt_i32_e64 s[74:75], 0, v10
	v_cmp_gt_i32_e64 s[80:81], 0, v11
	v_cmp_gt_i32_e64 s[66:67], 0, v8
	v_cmp_gt_i32_e64 s[72:73], 0, v9
	v_cmp_gt_i32_e64 s[58:59], 0, v6
	v_cmp_gt_i32_e64 s[64:65], 0, v7
	v_cmp_gt_i32_e64 s[50:51], 0, v4
	v_cmp_gt_i32_e64 s[56:57], 0, v5
	v_cmp_gt_i32_e64 s[0:1], 0, v2
	v_cmp_gt_i32_e64 s[48:49], 0, v3
	s_andn2_b64 vcc, exec, s[40:41]
	v_mov_b64_e32 v[66:67], v[50:51]
	v_mov_b64_e32 v[70:71], v[54:55]
	v_mov_b64_e32 v[74:75], v[58:59]
	v_mov_b64_e32 v[78:79], v[62:63]
	s_cbranch_vccnz .LBB0_441
	s_waitcnt vmcnt(3)
	v_mov_b64_e32 v[68:69], v[48:49]
	s_waitcnt vmcnt(2)
	v_mov_b64_e32 v[72:73], v[44:45]
	s_waitcnt vmcnt(1)
	v_mov_b64_e32 v[76:77], v[40:41]
	s_waitcnt vmcnt(0)
	v_mov_b64_e32 v[80:81], v[36:37]
	v_mov_b64_e32 v[66:67], v[46:47]
	v_mov_b64_e32 v[70:71], v[42:43]
	v_mov_b64_e32 v[74:75], v[38:39]
	v_mov_b64_e32 v[78:79], v[34:35]

; #define MFMA32(a, b, c) __builtin_amdgcn_mfma_f32_32x32x16_bf16((a), (b), (c), 0, 0, 0)
; DI void a1_task(unsigned char* shm, const bf16_t* prm, const bf16_t* prt, unsigned* mask, int b, int qt, const int tid) {
;     ...
;         const int kt = wid + 8 * jt;
;         if (kt <= qt) {
;             const int s0 = kt * 32;
;             bf16x8 kn[4];
;             const bool hn = (jt < 7) && (kt + 8 <= qt);
;             if (hn) {
; #pragma unroll
;                 for (int ks = 0; ks < 4; ++ks) kn[ks] = *(const bf16x8*)(kp + (size_t)(s0 + 256) * RM_LD + 16 * ks);
;             }
;             float idx[16];
; #pragma unroll
;             for (int i = 0; i < 16; ++i) idx[i] = 0.f;
;             const unsigned char* qb0 = shm + r * 1040 + 16 * h;
; #pragma unroll 2
;             for (int hh = 0; hh < 8; ++hh) {
;                 bf16x8 qa[4];
; #pragma unroll
;                 for (int ks = 0; ks < 4; ++ks) qa[ks] = *(const bf16x8*)(qb0 + hh * 128 + 32 * ks);
;                 const float wv = wqs[hh * 32 + r];
;                 asm volatile("s_waitcnt lgkmcnt(0)" ::: "memory");
;                 f32x16 acc;
; #pragma unroll
;                 for (int i = 0; i < 16; ++i) acc[i] = 0.f;
; #pragma unroll
;                 for (int ks = 0; ks < 4; ++ks) acc = MFMA32(kf[ks], qa[ks], acc);
; #pragma unroll
;                 for (int i = 0; i < 16; ++i) idx[i] = fmaf(wv, fmaxf(acc[i], 0.f), idx[i]);
;             }
; #pragma unroll
;             for (int i = 0; i < 16; ++i) {
;                 const int s = s0 + 16 * (i >> 3) + 8 * h + (i & 7);
;                 const unsigned u = __float_as_uint(idx[i] + 0.0f);
;                 const unsigned k = (u & 0x80000000u) ? ~u : (u | 0x80000000u);
;                 key[jt][i] = (s <= t0 + r) ? k : 0u;
;             }
;             if (hn) {
; #pragma unroll
;                 for (int ks = 0; ks < 4; ++ks) kf[ks] = kn[ks];
.LBB0_444:
	s_mov_b32 s4, s40
	v_writelane_b32 v255, s4, 60
	s_cmp_le_i32 s40, s2
	s_mov_b64 s[0:1], -1
	v_writelane_b32 v255, s5, 61
	s_cselect_b64 s[4:5], -1, 0
	v_writelane_b32 v255, s4, 62
	s_and_b64 vcc, exec, s[4:5]
	v_readfirstlane_b32 s40, v0
	v_writelane_b32 v255, s5, 63
	s_cbranch_vccz .LBB0_452
	v_readlane_b32 s0, v255, 60
	v_readlane_b32 s4, v255, 40
	s_lshl_b32 s0, s0, 5
	s_add_i32 s40, s4, 56
	s_cmp_le_i32 s40, s2
	s_cselect_b64 vcc, -1, 0
	s_cmp_gt_i32 s40, s2
	v_readlane_b32 s1, v255, 61
	v_readlane_b32 s5, v255, 41
	s_cbranch_scc1 .LBB0_447
	s_add_i32 s1, s0, 0x100
	v_mad_i64_i32 v[2:3], s[4:5], s1, v241, v[108:109]
	global_load_dwordx4 v[46:49], v[2:3], off offset:1920
	global_load_dwordx4 v[42:45], v[2:3], off offset:1952
	global_load_dwordx4 v[38:41], v[2:3], off offset:1984
	global_load_dwordx4 v[34:37], v[2:3], off offset:2016
.LBB0_447:
	v_mov_b32_e32 v18, 0
	s_mov_b32 s1, 0
	v_mov_b32_e32 v19, v18
	v_mov_b32_e32 v32, v18
	v_mov_b32_e32 v33, v18
	v_mov_b32_e32 v30, v18
	v_mov_b32_e32 v31, v18
	v_mov_b32_e32 v28, v18
	v_mov_b32_e32 v29, v18
	v_mov_b32_e32 v26, v18
	v_mov_b32_e32 v27, v18
	v_mov_b32_e32 v24, v18
	v_mov_b32_e32 v25, v18
	v_mov_b32_e32 v22, v18
	v_mov_b32_e32 v23, v18
	v_mov_b32_e32 v20, v18
	v_mov_b32_e32 v21, v18
.LBB0_448:
	v_add_u32_e32 v63, s1, v118
	ds_read_b128 v[2:5], v63
	ds_read_b128 v[50:53], v63 offset:32
	ds_read_b128 v[54:57], v63 offset:64
	ds_read_b128 v[58:61], v63 offset:96
	v_add_u32_e32 v64, s1, v135
	s_waitcnt lgkmcnt(3)
	v_mfma_f32_32x32x16_bf16 v[2:17], v[66:69], v[2:5], 0
	ds_read_b32 v62, v64
	s_waitcnt lgkmcnt(0)
	s_addk_i32 s1, 0x100
	s_cmpk_lg_i32 s1, 0x400
	s_waitcnt lgkmcnt(3)
	v_mfma_f32_32x32x16_bf16 v[2:17], v[70:73], v[50:53], v[2:17]
	s_waitcnt lgkmcnt(2)
	v_mfma_f32_32x32x16_bf16 v[2:17], v[74:77], v[54:57], v[2:17]
	s_waitcnt lgkmcnt(1)
	v_mfma_f32_32x32x16_bf16 v[2:17], v[78:81], v[58:61], v[2:17]
	s_nop 11
	v_max_f32_e32 v2, 0, v2
	v_max_f32_e32 v3, 0, v3
	s_waitcnt lgkmcnt(0)
	v_pk_fma_f32 v[32:33], v[62:63], v[2:3], v[32:33] op_sel_hi:[0,1,1]
	v_max_f32_e32 v2, 0, v4
	v_max_f32_e32 v3, 0, v5
	v_pk_fma_f32 v[30:31], v[62:63], v[2:3], v[30:31] op_sel_hi:[0,1,1]
	v_max_f32_e32 v2, 0, v6
	v_max_f32_e32 v3, 0, v7
	v_pk_fma_f32 v[28:29], v[62:63], v[2:3], v[28:29] op_sel_hi:[0,1,1]
	v_max_f32_e32 v2, 0, v8
	v_max_f32_e32 v3, 0, v9
	v_pk_fma_f32 v[26:27], v[62:63], v[2:3], v[26:27] op_sel_hi:[0,1,1]
	v_max_f32_e32 v2, 0, v10
	v_max_f32_e32 v3, 0, v11
	v_pk_fma_f32 v[24:25], v[62:63], v[2:3], v[24:25] op_sel_hi:[0,1,1]
	v_max_f32_e32 v2, 0, v12
	v_max_f32_e32 v3, 0, v13
	v_pk_fma_f32 v[22:23], v[62:63], v[2:3], v[22:23] op_sel_hi:[0,1,1]
	v_max_f32_e32 v2, 0, v14
	v_max_f32_e32 v3, 0, v15
	v_pk_fma_f32 v[20:21], v[62:63], v[2:3], v[20:21] op_sel_hi:[0,1,1]
	v_max_f32_e32 v2, 0, v16
	v_max_f32_e32 v3, 0, v17
	v_pk_fma_f32 v[18:19], v[62:63], v[2:3], v[18:19] op_sel_hi:[0,1,1]
	ds_read_b128 v[2:5], v63 offset:128
	ds_read_b128 v[50:53], v63 offset:160
	ds_read_b128 v[54:57], v63 offset:192
	ds_read_b128 v[58:61], v63 offset:224
	ds_read_b32 v62, v64 offset:128
	s_waitcnt lgkmcnt(4)
	v_mfma_f32_32x32x16_bf16 v[2:17], v[66:69], v[2:5], 0
	s_waitcnt lgkmcnt(0)
	s_waitcnt lgkmcnt(3)
	v_mfma_f32_32x32x16_bf16 v[2:17], v[70:73], v[50:53], v[2:17]
	s_waitcnt lgkmcnt(2)
	v_mfma_f32_32x32x16_bf16 v[2:17], v[74:77], v[54:57], v[2:17]
	s_waitcnt lgkmcnt(1)
	v_mfma_f32_32x32x16_bf16 v[2:17], v[78:81], v[58:61], v[2:17]
	s_nop 11
	v_max_f32_e32 v2, 0, v2
	v_max_f32_e32 v3, 0, v3
	s_waitcnt lgkmcnt(0)
	v_pk_fma_f32 v[32:33], v[62:63], v[2:3], v[32:33] op_sel_hi:[0,1,1]
	v_max_f32_e32 v2, 0, v4
	v_max_f32_e32 v3, 0, v5
	v_pk_fma_f32 v[30:31], v[62:63], v[2:3], v[30:31] op_sel_hi:[0,1,1]
	v_max_f32_e32 v2, 0, v6
	v_max_f32_e32 v3, 0, v7
	v_pk_fma_f32 v[28:29], v[62:63], v[2:3], v[28:29] op_sel_hi:[0,1,1]
	v_max_f32_e32 v2, 0, v8
	v_max_f32_e32 v3, 0, v9
	v_pk_fma_f32 v[26:27], v[62:63], v[2:3], v[26:27] op_sel_hi:[0,1,1]
	v_max_f32_e32 v2, 0, v10
	v_max_f32_e32 v3, 0, v11
	v_pk_fma_f32 v[24:25], v[62:63], v[2:3], v[24:25] op_sel_hi:[0,1,1]
	v_max_f32_e32 v2, 0, v12
	v_max_f32_e32 v3, 0, v13
	v_pk_fma_f32 v[22:23], v[62:63], v[2:3], v[22:23] op_sel_hi:[0,1,1]
	v_max_f32_e32 v2, 0, v14
	v_max_f32_e32 v3, 0, v15
	v_pk_fma_f32 v[20:21], v[62:63], v[2:3], v[20:21] op_sel_hi:[0,1,1]
	v_max_f32_e32 v2, 0, v16
	v_max_f32_e32 v3, 0, v17
	v_pk_fma_f32 v[18:19], v[62:63], v[2:3], v[18:19] op_sel_hi:[0,1,1]
	s_cbranch_scc1 .LBB0_448
	v_or_b32_e32 v50, s0, v98
	v_or_b32_e32 v2, 3, v50
	v_or_b32_e32 v3, 2, v50
	v_cmp_le_i32_e64 s[92:93], v3, v0
	v_cmp_le_i32_e64 s[94:95], v2, v0
	v_or_b32_e32 v2, 5, v50
	v_or_b32_e32 v3, 4, v50
	v_cmp_le_i32_e64 s[84:85], v3, v0
	v_cmp_le_i32_e64 s[86:87], v2, v0
	v_or_b32_e32 v2, 7, v50
	v_or_b32_e32 v3, 6, v50
	v_cmp_le_i32_e64 s[76:77], v3, v0
	v_cmp_le_i32_e64 s[78:79], v2, v0
	v_or_b32_e32 v2, 17, v50
	v_or_b32_e32 v3, 16, v50
	v_cmp_le_i32_e64 s[68:69], v3, v0
	v_cmp_le_i32_e64 s[70:71], v2, v0
	v_or_b32_e32 v2, 19, v50
	v_or_b32_e32 v3, 18, v50
	v_cmp_le_i32_e64 s[60:61], v3, v0
	v_cmp_le_i32_e64 s[62:63], v2, v0
	v_or_b32_e32 v2, 21, v50
	v_or_b32_e32 v3, 20, v50
	v_cmp_le_i32_e64 s[52:53], v3, v0
	v_cmp_le_i32_e64 s[54:55], v2, v0
	v_pk_add_f32 v[2:3], v[18:19], 0 op_sel_hi:[1,0]
	v_or_b32_e32 v18, 23, v50
	v_or_b32_e32 v19, 22, v50
	v_pk_add_f32 v[16:17], v[32:33], 0 op_sel_hi:[1,0]
	v_pk_add_f32 v[14:15], v[30:31], 0 op_sel_hi:[1,0]
	v_pk_add_f32 v[12:13], v[28:29], 0 op_sel_hi:[1,0]
	v_pk_add_f32 v[10:11], v[26:27], 0 op_sel_hi:[1,0]
	v_pk_add_f32 v[8:9], v[24:25], 0 op_sel_hi:[1,0]
	v_pk_add_f32 v[6:7], v[22:23], 0 op_sel_hi:[1,0]
	v_pk_add_f32 v[4:5], v[20:21], 0 op_sel_hi:[1,0]
	v_cmp_le_i32_e64 s[42:43], v19, v0
	v_cmp_le_i32_e64 s[44:45], v18, v0
	v_mov_b64_e32 v[18:19], v[66:67]
	v_mov_b64_e32 v[22:23], v[70:71]
	v_mov_b64_e32 v[26:27], v[74:75]
	v_mov_b64_e32 v[30:31], v[78:79]
	v_cmp_gt_i32_e64 s[96:97], 0, v17
	v_cmp_gt_i32_e64 s[6:7], 0, v16
	v_cmp_le_i32_e64 s[8:9], v50, v0
	v_cmp_lt_i32_e64 s[4:5], v50, v0
	v_cmp_gt_i32_e64 s[90:91], 0, v14
	v_cmp_gt_i32_e64 s[46:47], 0, v15
	v_cmp_gt_i32_e64 s[82:83], 0, v12
	v_cmp_gt_i32_e64 s[88:89], 0, v13
	v_cmp_gt_i32_e64 s[74:75], 0, v10
	v_cmp_gt_i32_e64 s[80:81], 0, v11
	v_cmp_gt_i32_e64 s[66:67], 0, v8
	v_cmp_gt_i32_e64 s[72:73], 0, v9
	v_cmp_gt_i32_e64 s[58:59], 0, v6
	v_cmp_gt_i32_e64 s[64:65], 0, v7
	v_cmp_gt_i32_e64 s[50:51], 0, v4
	v_cmp_gt_i32_e64 s[56:57], 0, v5
	v_cmp_gt_i32_e64 s[0:1], 0, v2
	v_cmp_gt_i32_e64 s[48:49], 0, v3
	s_andn2_b64 vcc, exec, vcc
	v_mov_b64_e32 v[20:21], v[68:69]
	v_mov_b64_e32 v[24:25], v[72:73]
	v_mov_b64_e32 v[28:29], v[76:77]
	v_mov_b64_e32 v[32:33], v[80:81]
	s_cbranch_vccnz .LBB0_451
	s_waitcnt vmcnt(0)
	v_mov_b64_e32 v[18:19], v[46:47]
	v_mov_b64_e32 v[22:23], v[42:43]
	v_mov_b64_e32 v[26:27], v[38:39]
	v_mov_b64_e32 v[30:31], v[34:35]
	v_mov_b64_e32 v[20:21], v[48:49]
	v_mov_b64_e32 v[24:25], v[44:45]
	v_mov_b64_e32 v[28:29], v[40:41]
	v_mov_b64_e32 v[32:33], v[36:37]

; #define MFMA32(a, b, c) __builtin_amdgcn_mfma_f32_32x32x16_bf16((a), (b), (c), 0, 0, 0)
; DI void a1_task(unsigned char* shm, const bf16_t* prm, const bf16_t* prt, unsigned* mask, int b, int qt, const int tid) {
;     ...
;             for (int hh = 0; hh < 8; ++hh) {
;                 bf16x8 qa[4];
; #pragma unroll
;                 for (int ks = 0; ks < 4; ++ks) qa[ks] = *(const bf16x8*)(qb0 + hh * 128 + 32 * ks);
;                 const float wv = wqs[hh * 32 + r];
;                 asm volatile("s_waitcnt lgkmcnt(0)" ::: "memory");
;                 f32x16 acc;
; #pragma unroll
;                 for (int i = 0; i < 16; ++i) acc[i] = 0.f;
; #pragma unroll
;                 for (int ks = 0; ks < 4; ++ks) acc = MFMA32(kf[ks], qa[ks], acc);
; #pragma unroll
;                 for (int i = 0; i < 16; ++i) idx[i] = fmaf(wv, fmaxf(acc[i], 0.f), idx[i]);
;             }
.LBB0_456:
	v_add_u32_e32 v79, s0, v118
	ds_read_b128 v[2:5], v79
	ds_read_b128 v[66:69], v79 offset:32
	ds_read_b128 v[70:73], v79 offset:64
	ds_read_b128 v[74:77], v79 offset:96
	v_add_u32_e32 v80, s0, v135
	s_waitcnt lgkmcnt(3)
	v_mfma_f32_32x32x16_bf16 v[2:17], v[18:21], v[2:5], 0
	ds_read_b32 v78, v80
	s_waitcnt lgkmcnt(0)
	s_addk_i32 s0, 0x100
	s_cmpk_lg_i32 s0, 0x400
	s_waitcnt lgkmcnt(3)
	v_mfma_f32_32x32x16_bf16 v[2:17], v[22:25], v[66:69], v[2:17]
	s_waitcnt lgkmcnt(2)
	v_mfma_f32_32x32x16_bf16 v[2:17], v[26:29], v[70:73], v[2:17]
	s_waitcnt lgkmcnt(1)
	v_mfma_f32_32x32x16_bf16 v[2:17], v[30:33], v[74:77], v[2:17]
	s_nop 11
	v_max_f32_e32 v2, 0, v2
	v_max_f32_e32 v3, 0, v3
	s_waitcnt lgkmcnt(0)
	v_pk_fma_f32 v[34:35], v[78:79], v[2:3], v[34:35] op_sel_hi:[0,1,1]
	v_max_f32_e32 v2, 0, v4
	v_max_f32_e32 v3, 0, v5
	v_pk_fma_f32 v[36:37], v[78:79], v[2:3], v[36:37] op_sel_hi:[0,1,1]
	v_max_f32_e32 v2, 0, v6
	v_max_f32_e32 v3, 0, v7
	v_pk_fma_f32 v[38:39], v[78:79], v[2:3], v[38:39] op_sel_hi:[0,1,1]
	v_max_f32_e32 v2, 0, v8
	v_max_f32_e32 v3, 0, v9
	v_pk_fma_f32 v[40:41], v[78:79], v[2:3], v[40:41] op_sel_hi:[0,1,1]
	v_max_f32_e32 v2, 0, v10
	v_max_f32_e32 v3, 0, v11
	v_pk_fma_f32 v[42:43], v[78:79], v[2:3], v[42:43] op_sel_hi:[0,1,1]
	v_max_f32_e32 v2, 0, v12
	v_max_f32_e32 v3, 0, v13
	v_pk_fma_f32 v[44:45], v[78:79], v[2:3], v[44:45] op_sel_hi:[0,1,1]
	v_max_f32_e32 v2, 0, v14
	v_max_f32_e32 v3, 0, v15
	v_pk_fma_f32 v[46:47], v[78:79], v[2:3], v[46:47] op_sel_hi:[0,1,1]
	v_max_f32_e32 v2, 0, v16
	v_max_f32_e32 v3, 0, v17
	v_pk_fma_f32 v[48:49], v[78:79], v[2:3], v[48:49] op_sel_hi:[0,1,1]
	ds_read_b128 v[2:5], v79 offset:128
	ds_read_b128 v[66:69], v79 offset:160
	ds_read_b128 v[70:73], v79 offset:192
	ds_read_b128 v[74:77], v79 offset:224
	ds_read_b32 v78, v80 offset:128
	s_waitcnt lgkmcnt(4)
	v_mfma_f32_32x32x16_bf16 v[2:17], v[18:21], v[2:5], 0
	s_waitcnt lgkmcnt(0)
	s_waitcnt lgkmcnt(3)
	v_mfma_f32_32x32x16_bf16 v[2:17], v[22:25], v[66:69], v[2:17]
	s_waitcnt lgkmcnt(2)
	v_mfma_f32_32x32x16_bf16 v[2:17], v[26:29], v[70:73], v[2:17]
	s_waitcnt lgkmcnt(1)
	v_mfma_f32_32x32x16_bf16 v[2:17], v[30:33], v[74:77], v[2:17]
	s_nop 11
	v_max_f32_e32 v2, 0, v2
	v_max_f32_e32 v3, 0, v3
	s_waitcnt lgkmcnt(0)
	v_pk_fma_f32 v[34:35], v[78:79], v[2:3], v[34:35] op_sel_hi:[0,1,1]
	v_max_f32_e32 v2, 0, v4
	v_max_f32_e32 v3, 0, v5
	v_pk_fma_f32 v[36:37], v[78:79], v[2:3], v[36:37] op_sel_hi:[0,1,1]
	v_max_f32_e32 v2, 0, v6
	v_max_f32_e32 v3, 0, v7
	v_pk_fma_f32 v[38:39], v[78:79], v[2:3], v[38:39] op_sel_hi:[0,1,1]
	v_max_f32_e32 v2, 0, v8
	v_max_f32_e32 v3, 0, v9
	v_pk_fma_f32 v[40:41], v[78:79], v[2:3], v[40:41] op_sel_hi:[0,1,1]
	v_max_f32_e32 v2, 0, v10
	v_max_f32_e32 v3, 0, v11
	v_pk_fma_f32 v[42:43], v[78:79], v[2:3], v[42:43] op_sel_hi:[0,1,1]
	v_max_f32_e32 v2, 0, v12
	v_max_f32_e32 v3, 0, v13
	v_pk_fma_f32 v[44:45], v[78:79], v[2:3], v[44:45] op_sel_hi:[0,1,1]
	v_max_f32_e32 v2, 0, v14
	v_max_f32_e32 v3, 0, v15
	v_pk_fma_f32 v[46:47], v[78:79], v[2:3], v[46:47] op_sel_hi:[0,1,1]
	v_max_f32_e32 v2, 0, v16
	v_max_f32_e32 v3, 0, v17
	v_pk_fma_f32 v[48:49], v[78:79], v[2:3], v[48:49] op_sel_hi:[0,1,1]
	s_cbranch_scc1 .LBB0_456
; DI void a1_task(unsigned char* shm, const bf16_t* prm, const bf16_t* prt, unsigned* mask, int b, int qt, const int tid) {
;     ...
;             for (int i = 0; i < 16; ++i) {
;                 const int s = s0 + 16 * (i >> 3) + 8 * h + (i & 7);
;                 const unsigned u = __float_as_uint(idx[i] + 0.0f);
;                 const unsigned k = (u & 0x80000000u) ? ~u : (u | 0x80000000u);
;                 key[jt][i] = (s <= t0 + r) ? k : 0u;
;             }
	v_pk_add_f32 v[2:3], v[48:49], 0 op_sel_hi:[1,0]
	v_lshl_or_b32 v18, s40, 5, v98
	v_and_b32_e32 v5, 0x7fffffff, v3
	v_and_b32_e32 v4, 0x7fffffff, v2
	v_xor_b32_e32 v8, -1, v3
	v_pk_add_f32 v[4:5], v[4:5], 0 neg_lo:[1,1] neg_hi:[1,1]
	v_cmp_gt_i32_e32 vcc, 0, v3
	v_or_b32_e32 v7, 22, v18
	v_xor_b32_e32 v9, -1, v2
	v_cndmask_b32_e32 v3, v5, v8, vcc
	v_cmp_gt_i32_e32 vcc, 0, v2
	v_or_b32_e32 v6, 23, v18
	v_or_b32_e32 v8, 21, v18
	v_cndmask_b32_e32 v2, v4, v9, vcc
	v_cmp_le_i32_e32 vcc, v7, v0
	v_or_b32_e32 v9, 20, v18
	s_nop 0
	v_cndmask_b32_e32 v5, 0, v2, vcc
	v_cmp_le_i32_e32 vcc, v6, v0
	s_nop 1
	v_cndmask_b32_e32 v4, 0, v3, vcc
	v_pk_add_f32 v[2:3], v[46:47], 0 op_sel_hi:[1,0]
	s_nop 0
	v_and_b32_e32 v7, 0x7fffffff, v3
	v_and_b32_e32 v6, 0x7fffffff, v2
	v_xor_b32_e32 v10, -1, v3
	v_pk_add_f32 v[6:7], v[6:7], 0 neg_lo:[1,1] neg_hi:[1,1]
	v_cmp_gt_i32_e32 vcc, 0, v3
	v_xor_b32_e32 v11, -1, v2
	s_nop 0
	v_cndmask_b32_e32 v3, v7, v10, vcc
	v_cmp_gt_i32_e32 vcc, 0, v2
	v_or_b32_e32 v10, 19, v18
	s_nop 0
	v_cndmask_b32_e32 v2, v6, v11, vcc
	v_cmp_le_i32_e32 vcc, v9, v0
	v_or_b32_e32 v11, 18, v18
	s_nop 0
	v_cndmask_b32_e32 v7, 0, v2, vcc
	v_cmp_le_i32_e32 vcc, v8, v0
	s_nop 1
	v_cndmask_b32_e32 v6, 0, v3, vcc
	v_pk_add_f32 v[2:3], v[44:45], 0 op_sel_hi:[1,0]
	s_nop 0
	v_and_b32_e32 v9, 0x7fffffff, v3
	v_and_b32_e32 v8, 0x7fffffff, v2
	v_xor_b32_e32 v12, -1, v3
	v_pk_add_f32 v[8:9], v[8:9], 0 neg_lo:[1,1] neg_hi:[1,1]
	v_cmp_gt_i32_e32 vcc, 0, v3
	v_xor_b32_e32 v13, -1, v2
	s_nop 0
	v_cndmask_b32_e32 v3, v9, v12, vcc
	v_cmp_gt_i32_e32 vcc, 0, v2
	v_or_b32_e32 v12, 17, v18
	s_nop 0
	v_cndmask_b32_e32 v2, v8, v13, vcc
	v_cmp_le_i32_e32 vcc, v11, v0
	v_or_b32_e32 v13, 16, v18
	s_nop 0
	v_cndmask_b32_e32 v9, 0, v2, vcc
	v_cmp_le_i32_e32 vcc, v10, v0
	s_nop 1
	v_cndmask_b32_e32 v8, 0, v3, vcc
	v_pk_add_f32 v[2:3], v[42:43], 0 op_sel_hi:[1,0]
	s_nop 0
	v_and_b32_e32 v11, 0x7fffffff, v3
	v_and_b32_e32 v10, 0x7fffffff, v2
	v_xor_b32_e32 v14, -1, v3
	v_pk_add_f32 v[10:11], v[10:11], 0 neg_lo:[1,1] neg_hi:[1,1]
	v_cmp_gt_i32_e32 vcc, 0, v3
	v_xor_b32_e32 v15, -1, v2
	s_nop 0
	v_cndmask_b32_e32 v3, v11, v14, vcc
	v_cmp_gt_i32_e32 vcc, 0, v2
	v_or_b32_e32 v14, 7, v18
	s_nop 0
	v_cndmask_b32_e32 v2, v10, v15, vcc
	v_cmp_le_i32_e32 vcc, v13, v0
	v_or_b32_e32 v15, 6, v18
	s_nop 0
	v_cndmask_b32_e32 v11, 0, v2, vcc
	v_cmp_le_i32_e32 vcc, v12, v0
	s_nop 1
	v_cndmask_b32_e32 v10, 0, v3, vcc
	v_pk_add_f32 v[2:3], v[40:41], 0 op_sel_hi:[1,0]
	s_nop 0
	v_and_b32_e32 v13, 0x7fffffff, v3
	v_and_b32_e32 v12, 0x7fffffff, v2
	v_xor_b32_e32 v16, -1, v3
	v_pk_add_f32 v[12:13], v[12:13], 0 neg_lo:[1,1] neg_hi:[1,1]
	v_cmp_gt_i32_e32 vcc, 0, v3
	v_xor_b32_e32 v17, -1, v2
	s_nop 0
	v_cndmask_b32_e32 v3, v13, v16, vcc
	v_cmp_gt_i32_e32 vcc, 0, v2
	v_or_b32_e32 v16, 5, v18
	s_nop 0
	v_cndmask_b32_e32 v2, v12, v17, vcc
	v_cmp_le_i32_e32 vcc, v15, v0
	v_or_b32_e32 v17, 4, v18
	s_nop 0
	v_cndmask_b32_e32 v13, 0, v2, vcc
	v_cmp_le_i32_e32 vcc, v14, v0
	s_nop 1
	v_cndmask_b32_e32 v12, 0, v3, vcc
	v_pk_add_f32 v[2:3], v[38:39], 0 op_sel_hi:[1,0]
	s_nop 0
	v_and_b32_e32 v15, 0x7fffffff, v3
	v_and_b32_e32 v14, 0x7fffffff, v2
	v_xor_b32_e32 v19, -1, v3
	v_pk_add_f32 v[14:15], v[14:15], 0 neg_lo:[1,1] neg_hi:[1,1]
	v_cmp_gt_i32_e32 vcc, 0, v3
	v_xor_b32_e32 v20, -1, v2
	s_nop 0
	v_cndmask_b32_e32 v3, v15, v19, vcc
	v_cmp_gt_i32_e32 vcc, 0, v2
	v_or_b32_e32 v19, 3, v18
	s_nop 0
	v_cndmask_b32_e32 v2, v14, v20, vcc
	v_cmp_le_i32_e32 vcc, v17, v0
	v_or_b32_e32 v20, 2, v18
	s_nop 0
	v_cndmask_b32_e32 v15, 0, v2, vcc
	v_cmp_le_i32_e32 vcc, v16, v0
	s_nop 1
	v_cndmask_b32_e32 v14, 0, v3, vcc
	v_pk_add_f32 v[2:3], v[36:37], 0 op_sel_hi:[1,0]
	s_nop 0
	v_and_b32_e32 v17, 0x7fffffff, v3
	v_and_b32_e32 v16, 0x7fffffff, v2
	v_xor_b32_e32 v21, -1, v3
	v_pk_add_f32 v[16:17], v[16:17], 0 neg_lo:[1,1] neg_hi:[1,1]
	v_cmp_gt_i32_e32 vcc, 0, v3
	v_xor_b32_e32 v22, -1, v2
	s_nop 0
	v_cndmask_b32_e32 v3, v17, v21, vcc
	v_cmp_gt_i32_e32 vcc, 0, v2
	s_nop 1
	v_cndmask_b32_e32 v2, v16, v22, vcc
	v_cmp_le_i32_e32 vcc, v20, v0
	s_nop 1
	v_cndmask_b32_e32 v17, 0, v2, vcc
	v_cmp_le_i32_e32 vcc, v19, v0
	s_nop 1
	v_cndmask_b32_e32 v16, 0, v3, vcc
	v_pk_add_f32 v[2:3], v[34:35], 0 op_sel_hi:[1,0]
	s_nop 0
	v_or_b32_e32 v19, 0x80000000, v3
	v_not_b32_e32 v20, v3
	v_cmp_gt_i32_e32 vcc, 0, v3
	s_nop 1
	v_cndmask_b32_e32 v3, v19, v20, vcc
	v_cmp_lt_i32_e32 vcc, v18, v0
	v_or_b32_e32 v19, 0x80000000, v2
	s_nop 0
	v_cndmask_b32_e32 v34, 0, v3, vcc
	v_not_b32_e32 v3, v2
	v_cmp_gt_i32_e32 vcc, 0, v2
	s_nop 1
	v_cndmask_b32_e32 v2, v19, v3, vcc
	v_cmp_le_i32_e32 vcc, v18, v0
	s_nop 1
	v_cndmask_b32_e32 v35, 0, v2, vcc
